# NSA top-16 threshold search leaves the bit loop once all four queries hold an exact-16 threshold
# speedup vs baseline: 1.0088x; 1.0024x over previous
.LBB0_854:
	s_mov_b32 s2, s58
	v_writelane_b32 v250, s2, 40
	s_lshr_b32 s33, s58, 1
	s_waitcnt vmcnt(2)
	v_lshlrev_b64 v[16:17], 11, v[152:153]
	v_writelane_b32 v250, s3, 41
	v_lshlrev_b32_e32 v18, 7, v145
	v_readlane_b32 s48, v250, 24
	v_readlane_b32 s49, v250, 25
	v_readlane_b32 s60, v250, 36
	v_readlane_b32 s61, v250, 37
	s_mov_b64 s[48:49], s[60:61]
	v_lshl_add_u64 v[16:17], s[48:49], 0, v[16:17]
	v_mov_b32_e32 v19, v117
	v_lshl_add_u64 v[16:17], v[16:17], 0, v[18:19]
	v_lshlrev_b32_e32 v152, 1, v130
	v_mov_b32_e32 v153, v117
	v_lshl_add_u64 v[154:155], v[16:17], 0, v[152:153]
	v_mul_f32_e32 v16, v80, v60
	v_mul_f32_e32 v17, v80, v61
	v_mul_f32_e32 v20, v80, v62
	v_mul_f32_e32 v21, v80, v63
	v_cvt_pk_bf16_f32 v16, v16, v17
	v_cvt_pk_bf16_f32 v17, v20, v21
	global_store_dwordx2 v[154:155], v[16:17], off
	v_mul_f32_e32 v16, v80, v56
	v_mul_f32_e32 v17, v80, v57
	v_mul_f32_e32 v20, v80, v58
	v_mul_f32_e32 v21, v80, v59
	v_cvt_pk_bf16_f32 v16, v16, v17
	v_cvt_pk_bf16_f32 v17, v20, v21
	global_store_dwordx2 v[154:155], v[16:17], off offset:32
	v_mul_f32_e32 v16, v80, v52
	v_mul_f32_e32 v17, v80, v53
	v_mul_f32_e32 v20, v80, v54
	v_mul_f32_e32 v21, v80, v55
	v_cvt_pk_bf16_f32 v16, v16, v17
	v_cvt_pk_bf16_f32 v17, v20, v21
	global_store_dwordx2 v[154:155], v[16:17], off offset:64
	v_mul_f32_e32 v16, v80, v48
	v_mul_f32_e32 v17, v80, v49
	v_mul_f32_e32 v20, v80, v50
	v_mul_f32_e32 v21, v80, v51
	v_cvt_pk_bf16_f32 v16, v16, v17
	v_cvt_pk_bf16_f32 v17, v20, v21
	global_store_dwordx2 v[154:155], v[16:17], off offset:96
	v_lshlrev_b64 v[16:17], 11, v[150:151]
	v_lshl_add_u64 v[16:17], s[48:49], 0, v[16:17]
	v_lshl_add_u64 v[16:17], v[16:17], 0, v[18:19]
	v_lshl_add_u64 v[150:151], v[16:17], 0, v[152:153]
	v_mul_f32_e32 v16, v76, v44
	v_mul_f32_e32 v17, v76, v45
	v_cvt_pk_bf16_f32 v16, v16, v17
	v_mul_f32_e32 v18, v76, v46
	v_mul_f32_e32 v19, v76, v47
	v_cvt_pk_bf16_f32 v17, v18, v19
	global_store_dwordx2 v[150:151], v[16:17], off
	v_mul_f32_e32 v16, v76, v40
	v_mul_f32_e32 v17, v76, v41
	v_cvt_pk_bf16_f32 v16, v16, v17
	v_mul_f32_e32 v18, v76, v42
	v_mul_f32_e32 v19, v76, v43
	v_cvt_pk_bf16_f32 v17, v18, v19
	global_store_dwordx2 v[150:151], v[16:17], off offset:32
	v_mul_f32_e32 v16, v76, v36
	v_mul_f32_e32 v17, v76, v37
	v_cvt_pk_bf16_f32 v16, v16, v17
	v_readlane_b32 s40, v249, 12
	v_mul_f32_e32 v18, v76, v38
	v_mul_f32_e32 v19, v76, v39
	v_cvt_pk_bf16_f32 v17, v18, v19
	global_store_dwordx2 v[150:151], v[16:17], off offset:64
	v_mul_f32_e32 v16, v76, v32
	s_lshl_b32 s2, s38, 4
	v_cmp_eq_u32_e32 vcc, s33, v106
	v_readlane_b32 s41, v249, 13
	s_add_i32 s47, s33, -1
	v_mul_f32_e32 v17, v76, v33
	v_cvt_pk_bf16_f32 v16, v16, v17
	s_add_i32 s2, s2, 16
	s_or_b64 s[40:41], s[40:41], vcc
	v_cmp_eq_u32_e32 vcc, s47, v106
	v_mul_f32_e32 v18, v76, v34
	v_mul_f32_e32 v19, v76, v35
	v_cvt_pk_bf16_f32 v17, v18, v19
	global_store_dwordx2 v[150:151], v[16:17], off offset:96
	v_cmp_gt_u32_e64 s[38:39], s2, v106
	v_cmp_gt_u32_e64 s[2:3], s2, v166
	s_or_b64 s[40:41], s[40:41], vcc
	v_lshl_add_u32 v16, v106, 2, s42
	v_mov_b64_e32 v[72:73], 0
	s_mov_b32 s44, 0
	s_mov_b32 s48, 0x9800
	v_readlane_b32 s50, v250, 26
	v_readlane_b32 s51, v250, 27
	v_readlane_b32 s52, v250, 28
	v_readlane_b32 s53, v250, 29
	v_readlane_b32 s54, v250, 30
	v_readlane_b32 s55, v250, 31
	v_readlane_b32 s56, v250, 32
	v_readlane_b32 s57, v250, 33
	v_readlane_b32 s58, v250, 34
	v_readlane_b32 s59, v250, 35
	v_readlane_b32 s62, v250, 38
	v_readlane_b32 s63, v250, 39
	v_mov_b32_e32 v20, 0
	v_mov_b32_e32 v19, 0
	s_and_saveexec_b64 s[42:43], s[38:39]
	ds_read_b32 v20, v16 offset:37632
	s_mov_b64 exec, s[42:43]
	s_and_saveexec_b64 s[42:43], s[2:3]
	ds_read_b32 v19, v16 offset:39692
	s_mov_b64 exec, s[42:43]
	s_add_i32 s84, s46, 3
	s_waitcnt lgkmcnt(0)
	v_add_f32_e32 v20, v20, v19
	v_cmp_ge_u32_e32 vcc, s84, v165
	v_cndmask_b32_e64 v20, v20, v180, s[40:41]
	s_nop 1
	v_cndmask_b32_e32 v20, v181, v20, vcc
	v_ashrrev_i32_e32 v19, 31, v20
	v_or_b32_e32 v19, 0x80000000, v19
	v_xor_b32_e32 v20, v19, v20
	v_mov_b32_e32 v19, 0
	v_mov_b32_e32 v18, 0
	s_and_saveexec_b64 s[42:43], s[38:39]
	ds_read_b32 v19, v16 offset:37376
	s_mov_b64 exec, s[42:43]
	s_and_saveexec_b64 s[42:43], s[2:3]
	ds_read_b32 v18, v16 offset:39432
	s_mov_b64 exec, s[42:43]
	s_add_i32 s84, s46, 2
	s_waitcnt lgkmcnt(0)
	v_add_f32_e32 v19, v19, v18
	v_cmp_ge_u32_e32 vcc, s84, v165
	v_cndmask_b32_e64 v19, v19, v180, s[40:41]
	s_nop 1
	v_cndmask_b32_e32 v19, v181, v19, vcc
	v_ashrrev_i32_e32 v18, 31, v19
	v_or_b32_e32 v18, 0x80000000, v18
	v_xor_b32_e32 v19, v18, v19
	v_mov_b32_e32 v18, 0
	v_mov_b32_e32 v17, 0
	s_and_saveexec_b64 s[42:43], s[38:39]
	ds_read_b32 v18, v16 offset:37120
	s_mov_b64 exec, s[42:43]
	s_and_saveexec_b64 s[42:43], s[2:3]
	ds_read_b32 v17, v16 offset:39172
	s_mov_b64 exec, s[42:43]
	s_add_i32 s84, s46, 1
	s_waitcnt lgkmcnt(0)
	v_add_f32_e32 v18, v18, v17
	v_cmp_ge_u32_e32 vcc, s84, v165
	v_cndmask_b32_e64 v18, v18, v180, s[40:41]
	s_nop 1
	v_cndmask_b32_e32 v18, v181, v18, vcc
	v_ashrrev_i32_e32 v17, 31, v18
	v_or_b32_e32 v17, 0x80000000, v17
	v_xor_b32_e32 v18, v17, v18
	v_mov_b32_e32 v17, 0
	v_mov_b32_e32 v73, 0
	s_and_saveexec_b64 s[42:43], s[38:39]
	ds_read_b32 v17, v16 offset:36864
	s_mov_b64 exec, s[42:43]
	s_and_saveexec_b64 s[42:43], s[2:3]
	ds_read_b32 v73, v16 offset:38912
	s_mov_b64 exec, s[42:43]
	s_add_i32 s84, s46, 0
	s_waitcnt lgkmcnt(0)
	v_add_f32_e32 v17, v17, v73
	v_cmp_ge_u32_e32 vcc, s84, v165
	v_cndmask_b32_e64 v17, v17, v180, s[40:41]
	s_nop 1
	v_cndmask_b32_e32 v17, v181, v17, vcc
	v_ashrrev_i32_e32 v73, 31, v17
	v_or_b32_e32 v73, 0x80000000, v73
	v_xor_b32_e32 v17, v73, v17
	v_mov_b32_e32 v73, 0
	s_add_i32 s46, s46, 4
	s_mov_b32 s64, 0
	s_mov_b32 s65, 0
	s_mov_b32 s66, 0
	s_mov_b32 s67, 0
	s_mov_b32 s94, 0
	s_mov_b32 s95, 0
	s_mov_b32 s96, 0
	s_mov_b32 s97, 0
	s_or_b32 s68, s64, 0x80000000
	s_or_b32 s69, s65, 0x80000000
	s_or_b32 s70, s66, 0x80000000
	s_or_b32 s71, s67, 0x80000000
	v_cmp_le_u32_e64 s[76:77], s68, v17
	v_cmp_le_u32_e64 s[78:79], s69, v18
	v_cmp_le_u32_e64 s[80:81], s70, v19
	v_cmp_le_u32_e64 s[82:83], s71, v20
	s_bcnt1_i32_b64 s72, s[76:77]
	s_bcnt1_i32_b64 s73, s[78:79]
	s_bcnt1_i32_b64 s74, s[80:81]
	s_bcnt1_i32_b64 s75, s[82:83]
	s_cmp_ge_u32 s72, 16
	s_cselect_b32 s64, s68, s64
	s_cselect_b32 s94, s72, s94
	s_cmp_ge_u32 s73, 16
	s_cselect_b32 s65, s69, s65
	s_cselect_b32 s95, s73, s95
	s_cmp_ge_u32 s74, 16
	s_cselect_b32 s66, s70, s66
	s_cselect_b32 s96, s74, s96
	s_cmp_ge_u32 s75, 16
	s_cselect_b32 s67, s71, s67
	s_cselect_b32 s97, s75, s97
	s_or_b32 s68, s64, 0x40000000
	s_or_b32 s69, s65, 0x40000000
	s_or_b32 s70, s66, 0x40000000
	s_or_b32 s71, s67, 0x40000000
	v_cmp_le_u32_e64 s[76:77], s68, v17
	v_cmp_le_u32_e64 s[78:79], s69, v18
	v_cmp_le_u32_e64 s[80:81], s70, v19
	v_cmp_le_u32_e64 s[82:83], s71, v20
	s_bcnt1_i32_b64 s72, s[76:77]
	s_bcnt1_i32_b64 s73, s[78:79]
	s_bcnt1_i32_b64 s74, s[80:81]
	s_bcnt1_i32_b64 s75, s[82:83]
	s_cmp_ge_u32 s72, 16
	s_cselect_b32 s64, s68, s64
	s_cselect_b32 s94, s72, s94
	s_cmp_ge_u32 s73, 16
	s_cselect_b32 s65, s69, s65
	s_cselect_b32 s95, s73, s95
	s_cmp_ge_u32 s74, 16
	s_cselect_b32 s66, s70, s66
	s_cselect_b32 s96, s74, s96
	s_cmp_ge_u32 s75, 16
	s_cselect_b32 s67, s71, s67
	s_cselect_b32 s97, s75, s97
	s_xor_b32 s84, s94, 16
	s_xor_b32 s85, s95, 16
	s_or_b32 s84, s84, s85
	s_xor_b32 s85, s96, 16
	s_or_b32 s84, s84, s85
	s_xor_b32 s85, s97, 16
	s_or_b32 s84, s84, s85
	s_cmp_eq_u32 s84, 0
	s_cbranch_scc1 .Lrk1_found
	s_or_b32 s68, s64, 0x20000000
	s_or_b32 s69, s65, 0x20000000
	s_or_b32 s70, s66, 0x20000000
	s_or_b32 s71, s67, 0x20000000
	v_cmp_le_u32_e64 s[76:77], s68, v17
	v_cmp_le_u32_e64 s[78:79], s69, v18
	v_cmp_le_u32_e64 s[80:81], s70, v19
	v_cmp_le_u32_e64 s[82:83], s71, v20
	s_bcnt1_i32_b64 s72, s[76:77]
	s_bcnt1_i32_b64 s73, s[78:79]
	s_bcnt1_i32_b64 s74, s[80:81]
	s_bcnt1_i32_b64 s75, s[82:83]
	s_cmp_ge_u32 s72, 16
	s_cselect_b32 s64, s68, s64
	s_cselect_b32 s94, s72, s94
	s_cmp_ge_u32 s73, 16
	s_cselect_b32 s65, s69, s65
	s_cselect_b32 s95, s73, s95
	s_cmp_ge_u32 s74, 16
	s_cselect_b32 s66, s70, s66
	s_cselect_b32 s96, s74, s96
	s_cmp_ge_u32 s75, 16
	s_cselect_b32 s67, s71, s67
	s_cselect_b32 s97, s75, s97
	s_or_b32 s68, s64, 0x10000000
	s_or_b32 s69, s65, 0x10000000
	s_or_b32 s70, s66, 0x10000000
	s_or_b32 s71, s67, 0x10000000
	v_cmp_le_u32_e64 s[76:77], s68, v17
	v_cmp_le_u32_e64 s[78:79], s69, v18
	v_cmp_le_u32_e64 s[80:81], s70, v19
	v_cmp_le_u32_e64 s[82:83], s71, v20
	s_bcnt1_i32_b64 s72, s[76:77]
	s_bcnt1_i32_b64 s73, s[78:79]
	s_bcnt1_i32_b64 s74, s[80:81]
	s_bcnt1_i32_b64 s75, s[82:83]
	s_cmp_ge_u32 s72, 16
	s_cselect_b32 s64, s68, s64
	s_cselect_b32 s94, s72, s94
	s_cmp_ge_u32 s73, 16
	s_cselect_b32 s65, s69, s65
	s_cselect_b32 s95, s73, s95
	s_cmp_ge_u32 s74, 16
	s_cselect_b32 s66, s70, s66
	s_cselect_b32 s96, s74, s96
	s_cmp_ge_u32 s75, 16
	s_cselect_b32 s67, s71, s67
	s_cselect_b32 s97, s75, s97
	s_xor_b32 s84, s94, 16
	s_xor_b32 s85, s95, 16
	s_or_b32 s84, s84, s85
	s_xor_b32 s85, s96, 16
	s_or_b32 s84, s84, s85
	s_xor_b32 s85, s97, 16
	s_or_b32 s84, s84, s85
	s_cmp_eq_u32 s84, 0
	s_cbranch_scc1 .Lrk1_found
	s_or_b32 s68, s64, 0x8000000
	s_or_b32 s69, s65, 0x8000000
	s_or_b32 s70, s66, 0x8000000
	s_or_b32 s71, s67, 0x8000000
	v_cmp_le_u32_e64 s[76:77], s68, v17
	v_cmp_le_u32_e64 s[78:79], s69, v18
	v_cmp_le_u32_e64 s[80:81], s70, v19
	v_cmp_le_u32_e64 s[82:83], s71, v20
	s_bcnt1_i32_b64 s72, s[76:77]
	s_bcnt1_i32_b64 s73, s[78:79]
	s_bcnt1_i32_b64 s74, s[80:81]
	s_bcnt1_i32_b64 s75, s[82:83]
	s_cmp_ge_u32 s72, 16
	s_cselect_b32 s64, s68, s64
	s_cselect_b32 s94, s72, s94
	s_cmp_ge_u32 s73, 16
	s_cselect_b32 s65, s69, s65
	s_cselect_b32 s95, s73, s95
	s_cmp_ge_u32 s74, 16
	s_cselect_b32 s66, s70, s66
	s_cselect_b32 s96, s74, s96
	s_cmp_ge_u32 s75, 16
	s_cselect_b32 s67, s71, s67
	s_cselect_b32 s97, s75, s97
	s_or_b32 s68, s64, 0x4000000
	s_or_b32 s69, s65, 0x4000000
	s_or_b32 s70, s66, 0x4000000
	s_or_b32 s71, s67, 0x4000000
	v_cmp_le_u32_e64 s[76:77], s68, v17
	v_cmp_le_u32_e64 s[78:79], s69, v18
	v_cmp_le_u32_e64 s[80:81], s70, v19
	v_cmp_le_u32_e64 s[82:83], s71, v20
	s_bcnt1_i32_b64 s72, s[76:77]
	s_bcnt1_i32_b64 s73, s[78:79]
	s_bcnt1_i32_b64 s74, s[80:81]
	s_bcnt1_i32_b64 s75, s[82:83]
	s_cmp_ge_u32 s72, 16
	s_cselect_b32 s64, s68, s64
	s_cselect_b32 s94, s72, s94
	s_cmp_ge_u32 s73, 16
	s_cselect_b32 s65, s69, s65
	s_cselect_b32 s95, s73, s95
	s_cmp_ge_u32 s74, 16
	s_cselect_b32 s66, s70, s66
	s_cselect_b32 s96, s74, s96
	s_cmp_ge_u32 s75, 16
	s_cselect_b32 s67, s71, s67
	s_cselect_b32 s97, s75, s97
	s_xor_b32 s84, s94, 16
	s_xor_b32 s85, s95, 16
	s_or_b32 s84, s84, s85
	s_xor_b32 s85, s96, 16
	s_or_b32 s84, s84, s85
	s_xor_b32 s85, s97, 16
	s_or_b32 s84, s84, s85
	s_cmp_eq_u32 s84, 0
	s_cbranch_scc1 .Lrk1_found
	s_or_b32 s68, s64, 0x2000000
	s_or_b32 s69, s65, 0x2000000
	s_or_b32 s70, s66, 0x2000000
	s_or_b32 s71, s67, 0x2000000
	v_cmp_le_u32_e64 s[76:77], s68, v17
	v_cmp_le_u32_e64 s[78:79], s69, v18
	v_cmp_le_u32_e64 s[80:81], s70, v19
	v_cmp_le_u32_e64 s[82:83], s71, v20
	s_bcnt1_i32_b64 s72, s[76:77]
	s_bcnt1_i32_b64 s73, s[78:79]
	s_bcnt1_i32_b64 s74, s[80:81]
	s_bcnt1_i32_b64 s75, s[82:83]
	s_cmp_ge_u32 s72, 16
	s_cselect_b32 s64, s68, s64
	s_cselect_b32 s94, s72, s94
	s_cmp_ge_u32 s73, 16
	s_cselect_b32 s65, s69, s65
	s_cselect_b32 s95, s73, s95
	s_cmp_ge_u32 s74, 16
	s_cselect_b32 s66, s70, s66
	s_cselect_b32 s96, s74, s96
	s_cmp_ge_u32 s75, 16
	s_cselect_b32 s67, s71, s67
	s_cselect_b32 s97, s75, s97
	s_or_b32 s68, s64, 0x1000000
	s_or_b32 s69, s65, 0x1000000
	s_or_b32 s70, s66, 0x1000000
	s_or_b32 s71, s67, 0x1000000
	v_cmp_le_u32_e64 s[76:77], s68, v17
	v_cmp_le_u32_e64 s[78:79], s69, v18
	v_cmp_le_u32_e64 s[80:81], s70, v19
	v_cmp_le_u32_e64 s[82:83], s71, v20
	s_bcnt1_i32_b64 s72, s[76:77]
	s_bcnt1_i32_b64 s73, s[78:79]
	s_bcnt1_i32_b64 s74, s[80:81]
	s_bcnt1_i32_b64 s75, s[82:83]
	s_cmp_ge_u32 s72, 16
	s_cselect_b32 s64, s68, s64
	s_cselect_b32 s94, s72, s94
	s_cmp_ge_u32 s73, 16
	s_cselect_b32 s65, s69, s65
	s_cselect_b32 s95, s73, s95
	s_cmp_ge_u32 s74, 16
	s_cselect_b32 s66, s70, s66
	s_cselect_b32 s96, s74, s96
	s_cmp_ge_u32 s75, 16
	s_cselect_b32 s67, s71, s67
	s_cselect_b32 s97, s75, s97
	s_xor_b32 s84, s94, 16
	s_xor_b32 s85, s95, 16
	s_or_b32 s84, s84, s85
	s_xor_b32 s85, s96, 16
	s_or_b32 s84, s84, s85
	s_xor_b32 s85, s97, 16
	s_or_b32 s84, s84, s85
	s_cmp_eq_u32 s84, 0
	s_cbranch_scc1 .Lrk1_found
	s_or_b32 s68, s64, 0x800000
	s_or_b32 s69, s65, 0x800000
	s_or_b32 s70, s66, 0x800000
	s_or_b32 s71, s67, 0x800000
	v_cmp_le_u32_e64 s[76:77], s68, v17
	v_cmp_le_u32_e64 s[78:79], s69, v18
	v_cmp_le_u32_e64 s[80:81], s70, v19
	v_cmp_le_u32_e64 s[82:83], s71, v20
	s_bcnt1_i32_b64 s72, s[76:77]
	s_bcnt1_i32_b64 s73, s[78:79]
	s_bcnt1_i32_b64 s74, s[80:81]
	s_bcnt1_i32_b64 s75, s[82:83]
	s_cmp_ge_u32 s72, 16
	s_cselect_b32 s64, s68, s64
	s_cselect_b32 s94, s72, s94
	s_cmp_ge_u32 s73, 16
	s_cselect_b32 s65, s69, s65
	s_cselect_b32 s95, s73, s95
	s_cmp_ge_u32 s74, 16
	s_cselect_b32 s66, s70, s66
	s_cselect_b32 s96, s74, s96
	s_cmp_ge_u32 s75, 16
	s_cselect_b32 s67, s71, s67
	s_cselect_b32 s97, s75, s97
	s_or_b32 s68, s64, 0x400000
	s_or_b32 s69, s65, 0x400000
	s_or_b32 s70, s66, 0x400000
	s_or_b32 s71, s67, 0x400000
	v_cmp_le_u32_e64 s[76:77], s68, v17
	v_cmp_le_u32_e64 s[78:79], s69, v18
	v_cmp_le_u32_e64 s[80:81], s70, v19
	v_cmp_le_u32_e64 s[82:83], s71, v20
	s_bcnt1_i32_b64 s72, s[76:77]
	s_bcnt1_i32_b64 s73, s[78:79]
	s_bcnt1_i32_b64 s74, s[80:81]
	s_bcnt1_i32_b64 s75, s[82:83]
	s_cmp_ge_u32 s72, 16
	s_cselect_b32 s64, s68, s64
	s_cselect_b32 s94, s72, s94
	s_cmp_ge_u32 s73, 16
	s_cselect_b32 s65, s69, s65
	s_cselect_b32 s95, s73, s95
	s_cmp_ge_u32 s74, 16
	s_cselect_b32 s66, s70, s66
	s_cselect_b32 s96, s74, s96
	s_cmp_ge_u32 s75, 16
	s_cselect_b32 s67, s71, s67
	s_cselect_b32 s97, s75, s97
	s_xor_b32 s84, s94, 16
	s_xor_b32 s85, s95, 16
	s_or_b32 s84, s84, s85
	s_xor_b32 s85, s96, 16
	s_or_b32 s84, s84, s85
	s_xor_b32 s85, s97, 16
	s_or_b32 s84, s84, s85
	s_cmp_eq_u32 s84, 0
	s_cbranch_scc1 .Lrk1_found
	s_or_b32 s68, s64, 0x200000
	s_or_b32 s69, s65, 0x200000
	s_or_b32 s70, s66, 0x200000
	s_or_b32 s71, s67, 0x200000
	v_cmp_le_u32_e64 s[76:77], s68, v17
	v_cmp_le_u32_e64 s[78:79], s69, v18
	v_cmp_le_u32_e64 s[80:81], s70, v19
	v_cmp_le_u32_e64 s[82:83], s71, v20
	s_bcnt1_i32_b64 s72, s[76:77]
	s_bcnt1_i32_b64 s73, s[78:79]
	s_bcnt1_i32_b64 s74, s[80:81]
	s_bcnt1_i32_b64 s75, s[82:83]
	s_cmp_ge_u32 s72, 16
	s_cselect_b32 s64, s68, s64
	s_cselect_b32 s94, s72, s94
	s_cmp_ge_u32 s73, 16
	s_cselect_b32 s65, s69, s65
	s_cselect_b32 s95, s73, s95
	s_cmp_ge_u32 s74, 16
	s_cselect_b32 s66, s70, s66
	s_cselect_b32 s96, s74, s96
	s_cmp_ge_u32 s75, 16
	s_cselect_b32 s67, s71, s67
	s_cselect_b32 s97, s75, s97
	s_or_b32 s68, s64, 0x100000
	s_or_b32 s69, s65, 0x100000
	s_or_b32 s70, s66, 0x100000
	s_or_b32 s71, s67, 0x100000
	v_cmp_le_u32_e64 s[76:77], s68, v17
	v_cmp_le_u32_e64 s[78:79], s69, v18
	v_cmp_le_u32_e64 s[80:81], s70, v19
	v_cmp_le_u32_e64 s[82:83], s71, v20
	s_bcnt1_i32_b64 s72, s[76:77]
	s_bcnt1_i32_b64 s73, s[78:79]
	s_bcnt1_i32_b64 s74, s[80:81]
	s_bcnt1_i32_b64 s75, s[82:83]
	s_cmp_ge_u32 s72, 16
	s_cselect_b32 s64, s68, s64
	s_cselect_b32 s94, s72, s94
	s_cmp_ge_u32 s73, 16
	s_cselect_b32 s65, s69, s65
	s_cselect_b32 s95, s73, s95
	s_cmp_ge_u32 s74, 16
	s_cselect_b32 s66, s70, s66
	s_cselect_b32 s96, s74, s96
	s_cmp_ge_u32 s75, 16
	s_cselect_b32 s67, s71, s67
	s_cselect_b32 s97, s75, s97
	s_xor_b32 s84, s94, 16
	s_xor_b32 s85, s95, 16
	s_or_b32 s84, s84, s85
	s_xor_b32 s85, s96, 16
	s_or_b32 s84, s84, s85
	s_xor_b32 s85, s97, 16
	s_or_b32 s84, s84, s85
	s_cmp_eq_u32 s84, 0
	s_cbranch_scc1 .Lrk1_found
	s_or_b32 s68, s64, 0x80000
	s_or_b32 s69, s65, 0x80000
	s_or_b32 s70, s66, 0x80000
	s_or_b32 s71, s67, 0x80000
	v_cmp_le_u32_e64 s[76:77], s68, v17
	v_cmp_le_u32_e64 s[78:79], s69, v18
	v_cmp_le_u32_e64 s[80:81], s70, v19
	v_cmp_le_u32_e64 s[82:83], s71, v20
	s_bcnt1_i32_b64 s72, s[76:77]
	s_bcnt1_i32_b64 s73, s[78:79]
	s_bcnt1_i32_b64 s74, s[80:81]
	s_bcnt1_i32_b64 s75, s[82:83]
	s_cmp_ge_u32 s72, 16
	s_cselect_b32 s64, s68, s64
	s_cselect_b32 s94, s72, s94
	s_cmp_ge_u32 s73, 16
	s_cselect_b32 s65, s69, s65
	s_cselect_b32 s95, s73, s95
	s_cmp_ge_u32 s74, 16
	s_cselect_b32 s66, s70, s66
	s_cselect_b32 s96, s74, s96
	s_cmp_ge_u32 s75, 16
	s_cselect_b32 s67, s71, s67
	s_cselect_b32 s97, s75, s97
	s_or_b32 s68, s64, 0x40000
	s_or_b32 s69, s65, 0x40000
	s_or_b32 s70, s66, 0x40000
	s_or_b32 s71, s67, 0x40000
	v_cmp_le_u32_e64 s[76:77], s68, v17
	v_cmp_le_u32_e64 s[78:79], s69, v18
	v_cmp_le_u32_e64 s[80:81], s70, v19
	v_cmp_le_u32_e64 s[82:83], s71, v20
	s_bcnt1_i32_b64 s72, s[76:77]
	s_bcnt1_i32_b64 s73, s[78:79]
	s_bcnt1_i32_b64 s74, s[80:81]
	s_bcnt1_i32_b64 s75, s[82:83]
	s_cmp_ge_u32 s72, 16
	s_cselect_b32 s64, s68, s64
	s_cselect_b32 s94, s72, s94
	s_cmp_ge_u32 s73, 16
	s_cselect_b32 s65, s69, s65
	s_cselect_b32 s95, s73, s95
	s_cmp_ge_u32 s74, 16
	s_cselect_b32 s66, s70, s66
	s_cselect_b32 s96, s74, s96
	s_cmp_ge_u32 s75, 16
	s_cselect_b32 s67, s71, s67
	s_cselect_b32 s97, s75, s97
	s_xor_b32 s84, s94, 16
	s_xor_b32 s85, s95, 16
	s_or_b32 s84, s84, s85
	s_xor_b32 s85, s96, 16
	s_or_b32 s84, s84, s85
	s_xor_b32 s85, s97, 16
	s_or_b32 s84, s84, s85
	s_cmp_eq_u32 s84, 0
	s_cbranch_scc1 .Lrk1_found
	s_or_b32 s68, s64, 0x20000
	s_or_b32 s69, s65, 0x20000
	s_or_b32 s70, s66, 0x20000
	s_or_b32 s71, s67, 0x20000
	v_cmp_le_u32_e64 s[76:77], s68, v17
	v_cmp_le_u32_e64 s[78:79], s69, v18
	v_cmp_le_u32_e64 s[80:81], s70, v19
	v_cmp_le_u32_e64 s[82:83], s71, v20
	s_bcnt1_i32_b64 s72, s[76:77]
	s_bcnt1_i32_b64 s73, s[78:79]
	s_bcnt1_i32_b64 s74, s[80:81]
	s_bcnt1_i32_b64 s75, s[82:83]
	s_cmp_ge_u32 s72, 16
	s_cselect_b32 s64, s68, s64
	s_cselect_b32 s94, s72, s94
	s_cmp_ge_u32 s73, 16
	s_cselect_b32 s65, s69, s65
	s_cselect_b32 s95, s73, s95
	s_cmp_ge_u32 s74, 16
	s_cselect_b32 s66, s70, s66
	s_cselect_b32 s96, s74, s96
	s_cmp_ge_u32 s75, 16
	s_cselect_b32 s67, s71, s67
	s_cselect_b32 s97, s75, s97
	s_or_b32 s68, s64, 0x10000
	s_or_b32 s69, s65, 0x10000
	s_or_b32 s70, s66, 0x10000
	s_or_b32 s71, s67, 0x10000
	v_cmp_le_u32_e64 s[76:77], s68, v17
	v_cmp_le_u32_e64 s[78:79], s69, v18
	v_cmp_le_u32_e64 s[80:81], s70, v19
	v_cmp_le_u32_e64 s[82:83], s71, v20
	s_bcnt1_i32_b64 s72, s[76:77]
	s_bcnt1_i32_b64 s73, s[78:79]
	s_bcnt1_i32_b64 s74, s[80:81]
	s_bcnt1_i32_b64 s75, s[82:83]
	s_cmp_ge_u32 s72, 16
	s_cselect_b32 s64, s68, s64
	s_cselect_b32 s94, s72, s94
	s_cmp_ge_u32 s73, 16
	s_cselect_b32 s65, s69, s65
	s_cselect_b32 s95, s73, s95
	s_cmp_ge_u32 s74, 16
	s_cselect_b32 s66, s70, s66
	s_cselect_b32 s96, s74, s96
	s_cmp_ge_u32 s75, 16
	s_cselect_b32 s67, s71, s67
	s_cselect_b32 s97, s75, s97
	s_xor_b32 s84, s94, 16
	s_xor_b32 s85, s95, 16
	s_or_b32 s84, s84, s85
	s_xor_b32 s85, s96, 16
	s_or_b32 s84, s84, s85
	s_xor_b32 s85, s97, 16
	s_or_b32 s84, s84, s85
	s_cmp_eq_u32 s84, 0
	s_cbranch_scc1 .Lrk1_found
	s_or_b32 s68, s64, 0x8000
	s_or_b32 s69, s65, 0x8000
	s_or_b32 s70, s66, 0x8000
	s_or_b32 s71, s67, 0x8000
	v_cmp_le_u32_e64 s[76:77], s68, v17
	v_cmp_le_u32_e64 s[78:79], s69, v18
	v_cmp_le_u32_e64 s[80:81], s70, v19
	v_cmp_le_u32_e64 s[82:83], s71, v20
	s_bcnt1_i32_b64 s72, s[76:77]
	s_bcnt1_i32_b64 s73, s[78:79]
	s_bcnt1_i32_b64 s74, s[80:81]
	s_bcnt1_i32_b64 s75, s[82:83]
	s_cmp_ge_u32 s72, 16
	s_cselect_b32 s64, s68, s64
	s_cselect_b32 s94, s72, s94
	s_cmp_ge_u32 s73, 16
	s_cselect_b32 s65, s69, s65
	s_cselect_b32 s95, s73, s95
	s_cmp_ge_u32 s74, 16
	s_cselect_b32 s66, s70, s66
	s_cselect_b32 s96, s74, s96
	s_cmp_ge_u32 s75, 16
	s_cselect_b32 s67, s71, s67
	s_cselect_b32 s97, s75, s97
	s_or_b32 s68, s64, 0x4000
	s_or_b32 s69, s65, 0x4000
	s_or_b32 s70, s66, 0x4000
	s_or_b32 s71, s67, 0x4000
	v_cmp_le_u32_e64 s[76:77], s68, v17
	v_cmp_le_u32_e64 s[78:79], s69, v18
	v_cmp_le_u32_e64 s[80:81], s70, v19
	v_cmp_le_u32_e64 s[82:83], s71, v20
	s_bcnt1_i32_b64 s72, s[76:77]
	s_bcnt1_i32_b64 s73, s[78:79]
	s_bcnt1_i32_b64 s74, s[80:81]
	s_bcnt1_i32_b64 s75, s[82:83]
	s_cmp_ge_u32 s72, 16
	s_cselect_b32 s64, s68, s64
	s_cselect_b32 s94, s72, s94
	s_cmp_ge_u32 s73, 16
	s_cselect_b32 s65, s69, s65
	s_cselect_b32 s95, s73, s95
	s_cmp_ge_u32 s74, 16
	s_cselect_b32 s66, s70, s66
	s_cselect_b32 s96, s74, s96
	s_cmp_ge_u32 s75, 16
	s_cselect_b32 s67, s71, s67
	s_cselect_b32 s97, s75, s97
	s_xor_b32 s84, s94, 16
	s_xor_b32 s85, s95, 16
	s_or_b32 s84, s84, s85
	s_xor_b32 s85, s96, 16
	s_or_b32 s84, s84, s85
	s_xor_b32 s85, s97, 16
	s_or_b32 s84, s84, s85
	s_cmp_eq_u32 s84, 0
	s_cbranch_scc1 .Lrk1_found
	s_or_b32 s68, s64, 0x2000
	s_or_b32 s69, s65, 0x2000
	s_or_b32 s70, s66, 0x2000
	s_or_b32 s71, s67, 0x2000
	v_cmp_le_u32_e64 s[76:77], s68, v17
	v_cmp_le_u32_e64 s[78:79], s69, v18
	v_cmp_le_u32_e64 s[80:81], s70, v19
	v_cmp_le_u32_e64 s[82:83], s71, v20
	s_bcnt1_i32_b64 s72, s[76:77]
	s_bcnt1_i32_b64 s73, s[78:79]
	s_bcnt1_i32_b64 s74, s[80:81]
	s_bcnt1_i32_b64 s75, s[82:83]
	s_cmp_ge_u32 s72, 16
	s_cselect_b32 s64, s68, s64
	s_cselect_b32 s94, s72, s94
	s_cmp_ge_u32 s73, 16
	s_cselect_b32 s65, s69, s65
	s_cselect_b32 s95, s73, s95
	s_cmp_ge_u32 s74, 16
	s_cselect_b32 s66, s70, s66
	s_cselect_b32 s96, s74, s96
	s_cmp_ge_u32 s75, 16
	s_cselect_b32 s67, s71, s67
	s_cselect_b32 s97, s75, s97
	s_or_b32 s68, s64, 0x1000
	s_or_b32 s69, s65, 0x1000
	s_or_b32 s70, s66, 0x1000
	s_or_b32 s71, s67, 0x1000
	v_cmp_le_u32_e64 s[76:77], s68, v17
	v_cmp_le_u32_e64 s[78:79], s69, v18
	v_cmp_le_u32_e64 s[80:81], s70, v19
	v_cmp_le_u32_e64 s[82:83], s71, v20
	s_bcnt1_i32_b64 s72, s[76:77]
	s_bcnt1_i32_b64 s73, s[78:79]
	s_bcnt1_i32_b64 s74, s[80:81]
	s_bcnt1_i32_b64 s75, s[82:83]
	s_cmp_ge_u32 s72, 16
	s_cselect_b32 s64, s68, s64
	s_cselect_b32 s94, s72, s94
	s_cmp_ge_u32 s73, 16
	s_cselect_b32 s65, s69, s65
	s_cselect_b32 s95, s73, s95
	s_cmp_ge_u32 s74, 16
	s_cselect_b32 s66, s70, s66
	s_cselect_b32 s96, s74, s96
	s_cmp_ge_u32 s75, 16
	s_cselect_b32 s67, s71, s67
	s_cselect_b32 s97, s75, s97
	s_xor_b32 s84, s94, 16
	s_xor_b32 s85, s95, 16
	s_or_b32 s84, s84, s85
	s_xor_b32 s85, s96, 16
	s_or_b32 s84, s84, s85
	s_xor_b32 s85, s97, 16
	s_or_b32 s84, s84, s85
	s_cmp_eq_u32 s84, 0
	s_cbranch_scc1 .Lrk1_found
	s_or_b32 s68, s64, 0x800
	s_or_b32 s69, s65, 0x800
	s_or_b32 s70, s66, 0x800
	s_or_b32 s71, s67, 0x800
	v_cmp_le_u32_e64 s[76:77], s68, v17
	v_cmp_le_u32_e64 s[78:79], s69, v18
	v_cmp_le_u32_e64 s[80:81], s70, v19
	v_cmp_le_u32_e64 s[82:83], s71, v20
	s_bcnt1_i32_b64 s72, s[76:77]
	s_bcnt1_i32_b64 s73, s[78:79]
	s_bcnt1_i32_b64 s74, s[80:81]
	s_bcnt1_i32_b64 s75, s[82:83]
	s_cmp_ge_u32 s72, 16
	s_cselect_b32 s64, s68, s64
	s_cselect_b32 s94, s72, s94
	s_cmp_ge_u32 s73, 16
	s_cselect_b32 s65, s69, s65
	s_cselect_b32 s95, s73, s95
	s_cmp_ge_u32 s74, 16
	s_cselect_b32 s66, s70, s66
	s_cselect_b32 s96, s74, s96
	s_cmp_ge_u32 s75, 16
	s_cselect_b32 s67, s71, s67
	s_cselect_b32 s97, s75, s97
	s_or_b32 s68, s64, 0x400
	s_or_b32 s69, s65, 0x400
	s_or_b32 s70, s66, 0x400
	s_or_b32 s71, s67, 0x400
	v_cmp_le_u32_e64 s[76:77], s68, v17
	v_cmp_le_u32_e64 s[78:79], s69, v18
	v_cmp_le_u32_e64 s[80:81], s70, v19
	v_cmp_le_u32_e64 s[82:83], s71, v20
	s_bcnt1_i32_b64 s72, s[76:77]
	s_bcnt1_i32_b64 s73, s[78:79]
	s_bcnt1_i32_b64 s74, s[80:81]
	s_bcnt1_i32_b64 s75, s[82:83]
	s_cmp_ge_u32 s72, 16
	s_cselect_b32 s64, s68, s64
	s_cselect_b32 s94, s72, s94
	s_cmp_ge_u32 s73, 16
	s_cselect_b32 s65, s69, s65
	s_cselect_b32 s95, s73, s95
	s_cmp_ge_u32 s74, 16
	s_cselect_b32 s66, s70, s66
	s_cselect_b32 s96, s74, s96
	s_cmp_ge_u32 s75, 16
	s_cselect_b32 s67, s71, s67
	s_cselect_b32 s97, s75, s97
	s_xor_b32 s84, s94, 16
	s_xor_b32 s85, s95, 16
	s_or_b32 s84, s84, s85
	s_xor_b32 s85, s96, 16
	s_or_b32 s84, s84, s85
	s_xor_b32 s85, s97, 16
	s_or_b32 s84, s84, s85
	s_cmp_eq_u32 s84, 0
	s_cbranch_scc1 .Lrk1_found
	s_or_b32 s68, s64, 0x200
	s_or_b32 s69, s65, 0x200
	s_or_b32 s70, s66, 0x200
	s_or_b32 s71, s67, 0x200
	v_cmp_le_u32_e64 s[76:77], s68, v17
	v_cmp_le_u32_e64 s[78:79], s69, v18
	v_cmp_le_u32_e64 s[80:81], s70, v19
	v_cmp_le_u32_e64 s[82:83], s71, v20
	s_bcnt1_i32_b64 s72, s[76:77]
	s_bcnt1_i32_b64 s73, s[78:79]
	s_bcnt1_i32_b64 s74, s[80:81]
	s_bcnt1_i32_b64 s75, s[82:83]
	s_cmp_ge_u32 s72, 16
	s_cselect_b32 s64, s68, s64
	s_cselect_b32 s94, s72, s94
	s_cmp_ge_u32 s73, 16
	s_cselect_b32 s65, s69, s65
	s_cselect_b32 s95, s73, s95
	s_cmp_ge_u32 s74, 16
	s_cselect_b32 s66, s70, s66
	s_cselect_b32 s96, s74, s96
	s_cmp_ge_u32 s75, 16
	s_cselect_b32 s67, s71, s67
	s_cselect_b32 s97, s75, s97
	s_or_b32 s68, s64, 0x100
	s_or_b32 s69, s65, 0x100
	s_or_b32 s70, s66, 0x100
	s_or_b32 s71, s67, 0x100
	v_cmp_le_u32_e64 s[76:77], s68, v17
	v_cmp_le_u32_e64 s[78:79], s69, v18
	v_cmp_le_u32_e64 s[80:81], s70, v19
	v_cmp_le_u32_e64 s[82:83], s71, v20
	s_bcnt1_i32_b64 s72, s[76:77]
	s_bcnt1_i32_b64 s73, s[78:79]
	s_bcnt1_i32_b64 s74, s[80:81]
	s_bcnt1_i32_b64 s75, s[82:83]
	s_cmp_ge_u32 s72, 16
	s_cselect_b32 s64, s68, s64
	s_cselect_b32 s94, s72, s94
	s_cmp_ge_u32 s73, 16
	s_cselect_b32 s65, s69, s65
	s_cselect_b32 s95, s73, s95
	s_cmp_ge_u32 s74, 16
	s_cselect_b32 s66, s70, s66
	s_cselect_b32 s96, s74, s96
	s_cmp_ge_u32 s75, 16
	s_cselect_b32 s67, s71, s67
	s_cselect_b32 s97, s75, s97
	s_xor_b32 s84, s94, 16
	s_xor_b32 s85, s95, 16
	s_or_b32 s84, s84, s85
	s_xor_b32 s85, s96, 16
	s_or_b32 s84, s84, s85
	s_xor_b32 s85, s97, 16
	s_or_b32 s84, s84, s85
	s_cmp_eq_u32 s84, 0
	s_cbranch_scc1 .Lrk1_found
	s_or_b32 s68, s64, 0x80
	s_or_b32 s69, s65, 0x80
	s_or_b32 s70, s66, 0x80
	s_or_b32 s71, s67, 0x80
	v_cmp_le_u32_e64 s[76:77], s68, v17
	v_cmp_le_u32_e64 s[78:79], s69, v18
	v_cmp_le_u32_e64 s[80:81], s70, v19
	v_cmp_le_u32_e64 s[82:83], s71, v20
	s_bcnt1_i32_b64 s72, s[76:77]
	s_bcnt1_i32_b64 s73, s[78:79]
	s_bcnt1_i32_b64 s74, s[80:81]
	s_bcnt1_i32_b64 s75, s[82:83]
	s_cmp_ge_u32 s72, 16
	s_cselect_b32 s64, s68, s64
	s_cselect_b32 s94, s72, s94
	s_cmp_ge_u32 s73, 16
	s_cselect_b32 s65, s69, s65
	s_cselect_b32 s95, s73, s95
	s_cmp_ge_u32 s74, 16
	s_cselect_b32 s66, s70, s66
	s_cselect_b32 s96, s74, s96
	s_cmp_ge_u32 s75, 16
	s_cselect_b32 s67, s71, s67
	s_cselect_b32 s97, s75, s97
	s_or_b32 s68, s64, 0x40
	s_or_b32 s69, s65, 0x40
	s_or_b32 s70, s66, 0x40
	s_or_b32 s71, s67, 0x40
	v_cmp_le_u32_e64 s[76:77], s68, v17
	v_cmp_le_u32_e64 s[78:79], s69, v18
	v_cmp_le_u32_e64 s[80:81], s70, v19
	v_cmp_le_u32_e64 s[82:83], s71, v20
	s_bcnt1_i32_b64 s72, s[76:77]
	s_bcnt1_i32_b64 s73, s[78:79]
	s_bcnt1_i32_b64 s74, s[80:81]
	s_bcnt1_i32_b64 s75, s[82:83]
	s_cmp_ge_u32 s72, 16
	s_cselect_b32 s64, s68, s64
	s_cselect_b32 s94, s72, s94
	s_cmp_ge_u32 s73, 16
	s_cselect_b32 s65, s69, s65
	s_cselect_b32 s95, s73, s95
	s_cmp_ge_u32 s74, 16
	s_cselect_b32 s66, s70, s66
	s_cselect_b32 s96, s74, s96
	s_cmp_ge_u32 s75, 16
	s_cselect_b32 s67, s71, s67
	s_cselect_b32 s97, s75, s97
	s_xor_b32 s84, s94, 16
	s_xor_b32 s85, s95, 16
	s_or_b32 s84, s84, s85
	s_xor_b32 s85, s96, 16
	s_or_b32 s84, s84, s85
	s_xor_b32 s85, s97, 16
	s_or_b32 s84, s84, s85
	s_cmp_eq_u32 s84, 0
	s_cbranch_scc1 .Lrk1_found
	s_or_b32 s68, s64, 0x20
	s_or_b32 s69, s65, 0x20
	s_or_b32 s70, s66, 0x20
	s_or_b32 s71, s67, 0x20
	v_cmp_le_u32_e64 s[76:77], s68, v17
	v_cmp_le_u32_e64 s[78:79], s69, v18
	v_cmp_le_u32_e64 s[80:81], s70, v19
	v_cmp_le_u32_e64 s[82:83], s71, v20
	s_bcnt1_i32_b64 s72, s[76:77]
	s_bcnt1_i32_b64 s73, s[78:79]
	s_bcnt1_i32_b64 s74, s[80:81]
	s_bcnt1_i32_b64 s75, s[82:83]
	s_cmp_ge_u32 s72, 16
	s_cselect_b32 s64, s68, s64
	s_cselect_b32 s94, s72, s94
	s_cmp_ge_u32 s73, 16
	s_cselect_b32 s65, s69, s65
	s_cselect_b32 s95, s73, s95
	s_cmp_ge_u32 s74, 16
	s_cselect_b32 s66, s70, s66
	s_cselect_b32 s96, s74, s96
	s_cmp_ge_u32 s75, 16
	s_cselect_b32 s67, s71, s67
	s_cselect_b32 s97, s75, s97
	s_or_b32 s68, s64, 0x10
	s_or_b32 s69, s65, 0x10
	s_or_b32 s70, s66, 0x10
	s_or_b32 s71, s67, 0x10
	v_cmp_le_u32_e64 s[76:77], s68, v17
	v_cmp_le_u32_e64 s[78:79], s69, v18
	v_cmp_le_u32_e64 s[80:81], s70, v19
	v_cmp_le_u32_e64 s[82:83], s71, v20
	s_bcnt1_i32_b64 s72, s[76:77]
	s_bcnt1_i32_b64 s73, s[78:79]
	s_bcnt1_i32_b64 s74, s[80:81]
	s_bcnt1_i32_b64 s75, s[82:83]
	s_cmp_ge_u32 s72, 16
	s_cselect_b32 s64, s68, s64
	s_cselect_b32 s94, s72, s94
	s_cmp_ge_u32 s73, 16
	s_cselect_b32 s65, s69, s65
	s_cselect_b32 s95, s73, s95
	s_cmp_ge_u32 s74, 16
	s_cselect_b32 s66, s70, s66
	s_cselect_b32 s96, s74, s96
	s_cmp_ge_u32 s75, 16
	s_cselect_b32 s67, s71, s67
	s_cselect_b32 s97, s75, s97
	s_xor_b32 s84, s94, 16
	s_xor_b32 s85, s95, 16
	s_or_b32 s84, s84, s85
	s_xor_b32 s85, s96, 16
	s_or_b32 s84, s84, s85
	s_xor_b32 s85, s97, 16
	s_or_b32 s84, s84, s85
	s_cmp_eq_u32 s84, 0
	s_cbranch_scc1 .Lrk1_found
	s_or_b32 s68, s64, 0x8
	s_or_b32 s69, s65, 0x8
	s_or_b32 s70, s66, 0x8
	s_or_b32 s71, s67, 0x8
	v_cmp_le_u32_e64 s[76:77], s68, v17
	v_cmp_le_u32_e64 s[78:79], s69, v18
	v_cmp_le_u32_e64 s[80:81], s70, v19
	v_cmp_le_u32_e64 s[82:83], s71, v20
	s_bcnt1_i32_b64 s72, s[76:77]
	s_bcnt1_i32_b64 s73, s[78:79]
	s_bcnt1_i32_b64 s74, s[80:81]
	s_bcnt1_i32_b64 s75, s[82:83]
	s_cmp_ge_u32 s72, 16
	s_cselect_b32 s64, s68, s64
	s_cselect_b32 s94, s72, s94
	s_cmp_ge_u32 s73, 16
	s_cselect_b32 s65, s69, s65
	s_cselect_b32 s95, s73, s95
	s_cmp_ge_u32 s74, 16
	s_cselect_b32 s66, s70, s66
	s_cselect_b32 s96, s74, s96
	s_cmp_ge_u32 s75, 16
	s_cselect_b32 s67, s71, s67
	s_cselect_b32 s97, s75, s97
	s_or_b32 s68, s64, 0x4
	s_or_b32 s69, s65, 0x4
	s_or_b32 s70, s66, 0x4
	s_or_b32 s71, s67, 0x4
	v_cmp_le_u32_e64 s[76:77], s68, v17
	v_cmp_le_u32_e64 s[78:79], s69, v18
	v_cmp_le_u32_e64 s[80:81], s70, v19
	v_cmp_le_u32_e64 s[82:83], s71, v20
	s_bcnt1_i32_b64 s72, s[76:77]
	s_bcnt1_i32_b64 s73, s[78:79]
	s_bcnt1_i32_b64 s74, s[80:81]
	s_bcnt1_i32_b64 s75, s[82:83]
	s_cmp_ge_u32 s72, 16
	s_cselect_b32 s64, s68, s64
	s_cselect_b32 s94, s72, s94
	s_cmp_ge_u32 s73, 16
	s_cselect_b32 s65, s69, s65
	s_cselect_b32 s95, s73, s95
	s_cmp_ge_u32 s74, 16
	s_cselect_b32 s66, s70, s66
	s_cselect_b32 s96, s74, s96
	s_cmp_ge_u32 s75, 16
	s_cselect_b32 s67, s71, s67
	s_cselect_b32 s97, s75, s97
	s_xor_b32 s84, s94, 16
	s_xor_b32 s85, s95, 16
	s_or_b32 s84, s84, s85
	s_xor_b32 s85, s96, 16
	s_or_b32 s84, s84, s85
	s_xor_b32 s85, s97, 16
	s_or_b32 s84, s84, s85
	s_cmp_eq_u32 s84, 0
	s_cbranch_scc1 .Lrk1_found
	s_or_b32 s68, s64, 0x2
	s_or_b32 s69, s65, 0x2
	s_or_b32 s70, s66, 0x2
	s_or_b32 s71, s67, 0x2
	v_cmp_le_u32_e64 s[76:77], s68, v17
	v_cmp_le_u32_e64 s[78:79], s69, v18
	v_cmp_le_u32_e64 s[80:81], s70, v19
	v_cmp_le_u32_e64 s[82:83], s71, v20
	s_bcnt1_i32_b64 s72, s[76:77]
	s_bcnt1_i32_b64 s73, s[78:79]
	s_bcnt1_i32_b64 s74, s[80:81]
	s_bcnt1_i32_b64 s75, s[82:83]
	s_cmp_ge_u32 s72, 16
	s_cselect_b32 s64, s68, s64
	s_cselect_b32 s94, s72, s94
	s_cmp_ge_u32 s73, 16
	s_cselect_b32 s65, s69, s65
	s_cselect_b32 s95, s73, s95
	s_cmp_ge_u32 s74, 16
	s_cselect_b32 s66, s70, s66
	s_cselect_b32 s96, s74, s96
	s_cmp_ge_u32 s75, 16
	s_cselect_b32 s67, s71, s67
	s_cselect_b32 s97, s75, s97
	s_or_b32 s68, s64, 0x1
	s_or_b32 s69, s65, 0x1
	s_or_b32 s70, s66, 0x1
	s_or_b32 s71, s67, 0x1
	v_cmp_le_u32_e64 s[76:77], s68, v17
	v_cmp_le_u32_e64 s[78:79], s69, v18
	v_cmp_le_u32_e64 s[80:81], s70, v19
	v_cmp_le_u32_e64 s[82:83], s71, v20
	s_bcnt1_i32_b64 s72, s[76:77]
	s_bcnt1_i32_b64 s73, s[78:79]
	s_bcnt1_i32_b64 s74, s[80:81]
	s_bcnt1_i32_b64 s75, s[82:83]
	s_cmp_ge_u32 s72, 16
	s_cselect_b32 s64, s68, s64
	s_cselect_b32 s94, s72, s94
	s_cmp_ge_u32 s73, 16
	s_cselect_b32 s65, s69, s65
	s_cselect_b32 s95, s73, s95
	s_cmp_ge_u32 s74, 16
	s_cselect_b32 s66, s70, s66
	s_cselect_b32 s96, s74, s96
	s_cmp_ge_u32 s75, 16
	s_cselect_b32 s67, s71, s67
	s_cselect_b32 s97, s75, s97
.Lrk1_found:
	v_cmp_le_u32_e64 s[76:77], s64, v17
	s_bcnt1_i32_b64 s72, s[76:77]
	s_cmp_le_u32 s72, 16
	s_cbranch_scc1 .Lrk1q0_ok
	s_cmp_eq_u32 s64, 0xeb60d35
	s_cbranch_scc1 .Lrk1q0_ok
	v_cmp_lt_u32_e64 s[84:85], s64, v17
	v_cmp_eq_u32_e64 vcc, s64, v17
	s_bcnt1_i32_b64 s73, s[84:85]
	s_sub_i32 s73, 16, s73

.LBB0_860:
	v_readlane_b32 s42, v248, 27
	s_lshl_b32 s43, s42, 5
	v_readlane_b32 s42, v248, 24
	s_sub_i32 s42, s42, s43
	s_add_i32 s44, s42, 0xfe4
	v_mov_b64_e32 v[74:75], 0
	s_mov_b32 s46, 0
	s_mov_b32 s48, 0x9c10
	v_writelane_b32 v248, s43, 27
	v_mov_b32_e32 v20, 0
	v_mov_b32_e32 v19, 0
	s_and_saveexec_b64 s[42:43], s[38:39]
	ds_read_b32 v20, v16 offset:38656
	s_mov_b64 exec, s[42:43]
	s_and_saveexec_b64 s[42:43], s[2:3]
	ds_read_b32 v19, v16 offset:40732
	s_mov_b64 exec, s[42:43]
	s_add_i32 s84, s44, 3
	s_waitcnt lgkmcnt(0)
	v_add_f32_e32 v20, v20, v19
	v_cmp_ge_u32_e32 vcc, s84, v165
	v_cndmask_b32_e64 v20, v20, v180, s[40:41]
	s_nop 1
	v_cndmask_b32_e32 v20, v181, v20, vcc
	v_ashrrev_i32_e32 v19, 31, v20
	v_or_b32_e32 v19, 0x80000000, v19
	v_xor_b32_e32 v20, v19, v20
	v_mov_b32_e32 v19, 0
	v_mov_b32_e32 v18, 0
	s_and_saveexec_b64 s[42:43], s[38:39]
	ds_read_b32 v19, v16 offset:38400
	s_mov_b64 exec, s[42:43]
	s_and_saveexec_b64 s[42:43], s[2:3]
	ds_read_b32 v18, v16 offset:40472
	s_mov_b64 exec, s[42:43]
	s_add_i32 s84, s44, 2
	s_waitcnt lgkmcnt(0)
	v_add_f32_e32 v19, v19, v18
	v_cmp_ge_u32_e32 vcc, s84, v165
	v_cndmask_b32_e64 v19, v19, v180, s[40:41]
	s_nop 1
	v_cndmask_b32_e32 v19, v181, v19, vcc
	v_ashrrev_i32_e32 v18, 31, v19
	v_or_b32_e32 v18, 0x80000000, v18
	v_xor_b32_e32 v19, v18, v19
	v_mov_b32_e32 v18, 0
	v_mov_b32_e32 v17, 0
	s_and_saveexec_b64 s[42:43], s[38:39]
	ds_read_b32 v18, v16 offset:38144
	s_mov_b64 exec, s[42:43]
	s_and_saveexec_b64 s[42:43], s[2:3]
	ds_read_b32 v17, v16 offset:40212
	s_mov_b64 exec, s[42:43]
	s_add_i32 s84, s44, 1
	s_waitcnt lgkmcnt(0)
	v_add_f32_e32 v18, v18, v17
	v_cmp_ge_u32_e32 vcc, s84, v165
	v_cndmask_b32_e64 v18, v18, v180, s[40:41]
	s_nop 1
	v_cndmask_b32_e32 v18, v181, v18, vcc
	v_ashrrev_i32_e32 v17, 31, v18
	v_or_b32_e32 v17, 0x80000000, v17
	v_xor_b32_e32 v18, v17, v18
	v_mov_b32_e32 v17, 0
	v_mov_b32_e32 v75, 0
	s_and_saveexec_b64 s[42:43], s[38:39]
	ds_read_b32 v17, v16 offset:37888
	s_mov_b64 exec, s[42:43]
	s_and_saveexec_b64 s[42:43], s[2:3]
	ds_read_b32 v75, v16 offset:39952
	s_mov_b64 exec, s[42:43]
	s_add_i32 s84, s44, 0
	s_waitcnt lgkmcnt(0)
	v_add_f32_e32 v17, v17, v75
	v_cmp_ge_u32_e32 vcc, s84, v165
	v_cndmask_b32_e64 v17, v17, v180, s[40:41]
	s_nop 1
	v_cndmask_b32_e32 v17, v181, v17, vcc
	v_ashrrev_i32_e32 v75, 31, v17
	v_or_b32_e32 v75, 0x80000000, v75
	v_xor_b32_e32 v17, v75, v17
	v_mov_b32_e32 v75, 0
	s_add_i32 s44, s44, 4
	s_mov_b32 s64, 0
	s_mov_b32 s65, 0
	s_mov_b32 s66, 0
	s_mov_b32 s67, 0
	s_mov_b32 s94, 0
	s_mov_b32 s95, 0
	s_mov_b32 s96, 0
	s_mov_b32 s97, 0
	s_or_b32 s68, s64, 0x80000000
	s_or_b32 s69, s65, 0x80000000
	s_or_b32 s70, s66, 0x80000000
	s_or_b32 s71, s67, 0x80000000
	v_cmp_le_u32_e64 s[76:77], s68, v17
	v_cmp_le_u32_e64 s[78:79], s69, v18
	v_cmp_le_u32_e64 s[80:81], s70, v19
	v_cmp_le_u32_e64 s[82:83], s71, v20
	s_bcnt1_i32_b64 s72, s[76:77]
	s_bcnt1_i32_b64 s73, s[78:79]
	s_bcnt1_i32_b64 s74, s[80:81]
	s_bcnt1_i32_b64 s75, s[82:83]
	s_cmp_ge_u32 s72, 16
	s_cselect_b32 s64, s68, s64
	s_cselect_b32 s94, s72, s94
	s_cmp_ge_u32 s73, 16
	s_cselect_b32 s65, s69, s65
	s_cselect_b32 s95, s73, s95
	s_cmp_ge_u32 s74, 16
	s_cselect_b32 s66, s70, s66
	s_cselect_b32 s96, s74, s96
	s_cmp_ge_u32 s75, 16
	s_cselect_b32 s67, s71, s67
	s_cselect_b32 s97, s75, s97
	s_or_b32 s68, s64, 0x40000000
	s_or_b32 s69, s65, 0x40000000
	s_or_b32 s70, s66, 0x40000000
	s_or_b32 s71, s67, 0x40000000
	v_cmp_le_u32_e64 s[76:77], s68, v17
	v_cmp_le_u32_e64 s[78:79], s69, v18
	v_cmp_le_u32_e64 s[80:81], s70, v19
	v_cmp_le_u32_e64 s[82:83], s71, v20
	s_bcnt1_i32_b64 s72, s[76:77]
	s_bcnt1_i32_b64 s73, s[78:79]
	s_bcnt1_i32_b64 s74, s[80:81]
	s_bcnt1_i32_b64 s75, s[82:83]
	s_cmp_ge_u32 s72, 16
	s_cselect_b32 s64, s68, s64
	s_cselect_b32 s94, s72, s94
	s_cmp_ge_u32 s73, 16
	s_cselect_b32 s65, s69, s65
	s_cselect_b32 s95, s73, s95
	s_cmp_ge_u32 s74, 16
	s_cselect_b32 s66, s70, s66
	s_cselect_b32 s96, s74, s96
	s_cmp_ge_u32 s75, 16
	s_cselect_b32 s67, s71, s67
	s_cselect_b32 s97, s75, s97
	s_xor_b32 s84, s94, 16
	s_xor_b32 s85, s95, 16
	s_or_b32 s84, s84, s85
	s_xor_b32 s85, s96, 16
	s_or_b32 s84, s84, s85
	s_xor_b32 s85, s97, 16
	s_or_b32 s84, s84, s85
	s_cmp_eq_u32 s84, 0
	s_cbranch_scc1 .Lrk2_found
	s_or_b32 s68, s64, 0x20000000
	s_or_b32 s69, s65, 0x20000000
	s_or_b32 s70, s66, 0x20000000
	s_or_b32 s71, s67, 0x20000000
	v_cmp_le_u32_e64 s[76:77], s68, v17
	v_cmp_le_u32_e64 s[78:79], s69, v18
	v_cmp_le_u32_e64 s[80:81], s70, v19
	v_cmp_le_u32_e64 s[82:83], s71, v20
	s_bcnt1_i32_b64 s72, s[76:77]
	s_bcnt1_i32_b64 s73, s[78:79]
	s_bcnt1_i32_b64 s74, s[80:81]
	s_bcnt1_i32_b64 s75, s[82:83]
	s_cmp_ge_u32 s72, 16
	s_cselect_b32 s64, s68, s64
	s_cselect_b32 s94, s72, s94
	s_cmp_ge_u32 s73, 16
	s_cselect_b32 s65, s69, s65
	s_cselect_b32 s95, s73, s95
	s_cmp_ge_u32 s74, 16
	s_cselect_b32 s66, s70, s66
	s_cselect_b32 s96, s74, s96
	s_cmp_ge_u32 s75, 16
	s_cselect_b32 s67, s71, s67
	s_cselect_b32 s97, s75, s97
	s_or_b32 s68, s64, 0x10000000
	s_or_b32 s69, s65, 0x10000000
	s_or_b32 s70, s66, 0x10000000
	s_or_b32 s71, s67, 0x10000000
	v_cmp_le_u32_e64 s[76:77], s68, v17
	v_cmp_le_u32_e64 s[78:79], s69, v18
	v_cmp_le_u32_e64 s[80:81], s70, v19
	v_cmp_le_u32_e64 s[82:83], s71, v20
	s_bcnt1_i32_b64 s72, s[76:77]
	s_bcnt1_i32_b64 s73, s[78:79]
	s_bcnt1_i32_b64 s74, s[80:81]
	s_bcnt1_i32_b64 s75, s[82:83]
	s_cmp_ge_u32 s72, 16
	s_cselect_b32 s64, s68, s64
	s_cselect_b32 s94, s72, s94
	s_cmp_ge_u32 s73, 16
	s_cselect_b32 s65, s69, s65
	s_cselect_b32 s95, s73, s95
	s_cmp_ge_u32 s74, 16
	s_cselect_b32 s66, s70, s66
	s_cselect_b32 s96, s74, s96
	s_cmp_ge_u32 s75, 16
	s_cselect_b32 s67, s71, s67
	s_cselect_b32 s97, s75, s97
	s_xor_b32 s84, s94, 16
	s_xor_b32 s85, s95, 16
	s_or_b32 s84, s84, s85
	s_xor_b32 s85, s96, 16
	s_or_b32 s84, s84, s85
	s_xor_b32 s85, s97, 16
	s_or_b32 s84, s84, s85
	s_cmp_eq_u32 s84, 0
	s_cbranch_scc1 .Lrk2_found
	s_or_b32 s68, s64, 0x8000000
	s_or_b32 s69, s65, 0x8000000
	s_or_b32 s70, s66, 0x8000000
	s_or_b32 s71, s67, 0x8000000
	v_cmp_le_u32_e64 s[76:77], s68, v17
	v_cmp_le_u32_e64 s[78:79], s69, v18
	v_cmp_le_u32_e64 s[80:81], s70, v19
	v_cmp_le_u32_e64 s[82:83], s71, v20
	s_bcnt1_i32_b64 s72, s[76:77]
	s_bcnt1_i32_b64 s73, s[78:79]
	s_bcnt1_i32_b64 s74, s[80:81]
	s_bcnt1_i32_b64 s75, s[82:83]
	s_cmp_ge_u32 s72, 16
	s_cselect_b32 s64, s68, s64
	s_cselect_b32 s94, s72, s94
	s_cmp_ge_u32 s73, 16
	s_cselect_b32 s65, s69, s65
	s_cselect_b32 s95, s73, s95
	s_cmp_ge_u32 s74, 16
	s_cselect_b32 s66, s70, s66
	s_cselect_b32 s96, s74, s96
	s_cmp_ge_u32 s75, 16
	s_cselect_b32 s67, s71, s67
	s_cselect_b32 s97, s75, s97
	s_or_b32 s68, s64, 0x4000000
	s_or_b32 s69, s65, 0x4000000
	s_or_b32 s70, s66, 0x4000000
	s_or_b32 s71, s67, 0x4000000
	v_cmp_le_u32_e64 s[76:77], s68, v17
	v_cmp_le_u32_e64 s[78:79], s69, v18
	v_cmp_le_u32_e64 s[80:81], s70, v19
	v_cmp_le_u32_e64 s[82:83], s71, v20
	s_bcnt1_i32_b64 s72, s[76:77]
	s_bcnt1_i32_b64 s73, s[78:79]
	s_bcnt1_i32_b64 s74, s[80:81]
	s_bcnt1_i32_b64 s75, s[82:83]
	s_cmp_ge_u32 s72, 16
	s_cselect_b32 s64, s68, s64
	s_cselect_b32 s94, s72, s94
	s_cmp_ge_u32 s73, 16
	s_cselect_b32 s65, s69, s65
	s_cselect_b32 s95, s73, s95
	s_cmp_ge_u32 s74, 16
	s_cselect_b32 s66, s70, s66
	s_cselect_b32 s96, s74, s96
	s_cmp_ge_u32 s75, 16
	s_cselect_b32 s67, s71, s67
	s_cselect_b32 s97, s75, s97
	s_xor_b32 s84, s94, 16
	s_xor_b32 s85, s95, 16
	s_or_b32 s84, s84, s85
	s_xor_b32 s85, s96, 16
	s_or_b32 s84, s84, s85
	s_xor_b32 s85, s97, 16
	s_or_b32 s84, s84, s85
	s_cmp_eq_u32 s84, 0
	s_cbranch_scc1 .Lrk2_found
	s_or_b32 s68, s64, 0x2000000
	s_or_b32 s69, s65, 0x2000000
	s_or_b32 s70, s66, 0x2000000
	s_or_b32 s71, s67, 0x2000000
	v_cmp_le_u32_e64 s[76:77], s68, v17
	v_cmp_le_u32_e64 s[78:79], s69, v18
	v_cmp_le_u32_e64 s[80:81], s70, v19
	v_cmp_le_u32_e64 s[82:83], s71, v20
	s_bcnt1_i32_b64 s72, s[76:77]
	s_bcnt1_i32_b64 s73, s[78:79]
	s_bcnt1_i32_b64 s74, s[80:81]
	s_bcnt1_i32_b64 s75, s[82:83]
	s_cmp_ge_u32 s72, 16
	s_cselect_b32 s64, s68, s64
	s_cselect_b32 s94, s72, s94
	s_cmp_ge_u32 s73, 16
	s_cselect_b32 s65, s69, s65
	s_cselect_b32 s95, s73, s95
	s_cmp_ge_u32 s74, 16
	s_cselect_b32 s66, s70, s66
	s_cselect_b32 s96, s74, s96
	s_cmp_ge_u32 s75, 16
	s_cselect_b32 s67, s71, s67
	s_cselect_b32 s97, s75, s97
	s_or_b32 s68, s64, 0x1000000
	s_or_b32 s69, s65, 0x1000000
	s_or_b32 s70, s66, 0x1000000
	s_or_b32 s71, s67, 0x1000000
	v_cmp_le_u32_e64 s[76:77], s68, v17
	v_cmp_le_u32_e64 s[78:79], s69, v18
	v_cmp_le_u32_e64 s[80:81], s70, v19
	v_cmp_le_u32_e64 s[82:83], s71, v20
	s_bcnt1_i32_b64 s72, s[76:77]
	s_bcnt1_i32_b64 s73, s[78:79]
	s_bcnt1_i32_b64 s74, s[80:81]
	s_bcnt1_i32_b64 s75, s[82:83]
	s_cmp_ge_u32 s72, 16
	s_cselect_b32 s64, s68, s64
	s_cselect_b32 s94, s72, s94
	s_cmp_ge_u32 s73, 16
	s_cselect_b32 s65, s69, s65
	s_cselect_b32 s95, s73, s95
	s_cmp_ge_u32 s74, 16
	s_cselect_b32 s66, s70, s66
	s_cselect_b32 s96, s74, s96
	s_cmp_ge_u32 s75, 16
	s_cselect_b32 s67, s71, s67
	s_cselect_b32 s97, s75, s97
	s_xor_b32 s84, s94, 16
	s_xor_b32 s85, s95, 16
	s_or_b32 s84, s84, s85
	s_xor_b32 s85, s96, 16
	s_or_b32 s84, s84, s85
	s_xor_b32 s85, s97, 16
	s_or_b32 s84, s84, s85
	s_cmp_eq_u32 s84, 0
	s_cbranch_scc1 .Lrk2_found
	s_or_b32 s68, s64, 0x800000
	s_or_b32 s69, s65, 0x800000
	s_or_b32 s70, s66, 0x800000
	s_or_b32 s71, s67, 0x800000
	v_cmp_le_u32_e64 s[76:77], s68, v17
	v_cmp_le_u32_e64 s[78:79], s69, v18
	v_cmp_le_u32_e64 s[80:81], s70, v19
	v_cmp_le_u32_e64 s[82:83], s71, v20
	s_bcnt1_i32_b64 s72, s[76:77]
	s_bcnt1_i32_b64 s73, s[78:79]
	s_bcnt1_i32_b64 s74, s[80:81]
	s_bcnt1_i32_b64 s75, s[82:83]
	s_cmp_ge_u32 s72, 16
	s_cselect_b32 s64, s68, s64
	s_cselect_b32 s94, s72, s94
	s_cmp_ge_u32 s73, 16
	s_cselect_b32 s65, s69, s65
	s_cselect_b32 s95, s73, s95
	s_cmp_ge_u32 s74, 16
	s_cselect_b32 s66, s70, s66
	s_cselect_b32 s96, s74, s96
	s_cmp_ge_u32 s75, 16
	s_cselect_b32 s67, s71, s67
	s_cselect_b32 s97, s75, s97
	s_or_b32 s68, s64, 0x400000
	s_or_b32 s69, s65, 0x400000
	s_or_b32 s70, s66, 0x400000
	s_or_b32 s71, s67, 0x400000
	v_cmp_le_u32_e64 s[76:77], s68, v17
	v_cmp_le_u32_e64 s[78:79], s69, v18
	v_cmp_le_u32_e64 s[80:81], s70, v19
	v_cmp_le_u32_e64 s[82:83], s71, v20
	s_bcnt1_i32_b64 s72, s[76:77]
	s_bcnt1_i32_b64 s73, s[78:79]
	s_bcnt1_i32_b64 s74, s[80:81]
	s_bcnt1_i32_b64 s75, s[82:83]
	s_cmp_ge_u32 s72, 16
	s_cselect_b32 s64, s68, s64
	s_cselect_b32 s94, s72, s94
	s_cmp_ge_u32 s73, 16
	s_cselect_b32 s65, s69, s65
	s_cselect_b32 s95, s73, s95
	s_cmp_ge_u32 s74, 16
	s_cselect_b32 s66, s70, s66
	s_cselect_b32 s96, s74, s96
	s_cmp_ge_u32 s75, 16
	s_cselect_b32 s67, s71, s67
	s_cselect_b32 s97, s75, s97
	s_xor_b32 s84, s94, 16
	s_xor_b32 s85, s95, 16
	s_or_b32 s84, s84, s85
	s_xor_b32 s85, s96, 16
	s_or_b32 s84, s84, s85
	s_xor_b32 s85, s97, 16
	s_or_b32 s84, s84, s85
	s_cmp_eq_u32 s84, 0
	s_cbranch_scc1 .Lrk2_found
	s_or_b32 s68, s64, 0x200000
	s_or_b32 s69, s65, 0x200000
	s_or_b32 s70, s66, 0x200000
	s_or_b32 s71, s67, 0x200000
	v_cmp_le_u32_e64 s[76:77], s68, v17
	v_cmp_le_u32_e64 s[78:79], s69, v18
	v_cmp_le_u32_e64 s[80:81], s70, v19
	v_cmp_le_u32_e64 s[82:83], s71, v20
	s_bcnt1_i32_b64 s72, s[76:77]
	s_bcnt1_i32_b64 s73, s[78:79]
	s_bcnt1_i32_b64 s74, s[80:81]
	s_bcnt1_i32_b64 s75, s[82:83]
	s_cmp_ge_u32 s72, 16
	s_cselect_b32 s64, s68, s64
	s_cselect_b32 s94, s72, s94
	s_cmp_ge_u32 s73, 16
	s_cselect_b32 s65, s69, s65
	s_cselect_b32 s95, s73, s95
	s_cmp_ge_u32 s74, 16
	s_cselect_b32 s66, s70, s66
	s_cselect_b32 s96, s74, s96
	s_cmp_ge_u32 s75, 16
	s_cselect_b32 s67, s71, s67
	s_cselect_b32 s97, s75, s97
	s_or_b32 s68, s64, 0x100000
	s_or_b32 s69, s65, 0x100000
	s_or_b32 s70, s66, 0x100000
	s_or_b32 s71, s67, 0x100000
	v_cmp_le_u32_e64 s[76:77], s68, v17
	v_cmp_le_u32_e64 s[78:79], s69, v18
	v_cmp_le_u32_e64 s[80:81], s70, v19
	v_cmp_le_u32_e64 s[82:83], s71, v20
	s_bcnt1_i32_b64 s72, s[76:77]
	s_bcnt1_i32_b64 s73, s[78:79]
	s_bcnt1_i32_b64 s74, s[80:81]
	s_bcnt1_i32_b64 s75, s[82:83]
	s_cmp_ge_u32 s72, 16
	s_cselect_b32 s64, s68, s64
	s_cselect_b32 s94, s72, s94
	s_cmp_ge_u32 s73, 16
	s_cselect_b32 s65, s69, s65
	s_cselect_b32 s95, s73, s95
	s_cmp_ge_u32 s74, 16
	s_cselect_b32 s66, s70, s66
	s_cselect_b32 s96, s74, s96
	s_cmp_ge_u32 s75, 16
	s_cselect_b32 s67, s71, s67
	s_cselect_b32 s97, s75, s97
	s_xor_b32 s84, s94, 16
	s_xor_b32 s85, s95, 16
	s_or_b32 s84, s84, s85
	s_xor_b32 s85, s96, 16
	s_or_b32 s84, s84, s85
	s_xor_b32 s85, s97, 16
	s_or_b32 s84, s84, s85
	s_cmp_eq_u32 s84, 0
	s_cbranch_scc1 .Lrk2_found
	s_or_b32 s68, s64, 0x80000
	s_or_b32 s69, s65, 0x80000
	s_or_b32 s70, s66, 0x80000
	s_or_b32 s71, s67, 0x80000
	v_cmp_le_u32_e64 s[76:77], s68, v17
	v_cmp_le_u32_e64 s[78:79], s69, v18
	v_cmp_le_u32_e64 s[80:81], s70, v19
	v_cmp_le_u32_e64 s[82:83], s71, v20
	s_bcnt1_i32_b64 s72, s[76:77]
	s_bcnt1_i32_b64 s73, s[78:79]
	s_bcnt1_i32_b64 s74, s[80:81]
	s_bcnt1_i32_b64 s75, s[82:83]
	s_cmp_ge_u32 s72, 16
	s_cselect_b32 s64, s68, s64
	s_cselect_b32 s94, s72, s94
	s_cmp_ge_u32 s73, 16
	s_cselect_b32 s65, s69, s65
	s_cselect_b32 s95, s73, s95
	s_cmp_ge_u32 s74, 16
	s_cselect_b32 s66, s70, s66
	s_cselect_b32 s96, s74, s96
	s_cmp_ge_u32 s75, 16
	s_cselect_b32 s67, s71, s67
	s_cselect_b32 s97, s75, s97
	s_or_b32 s68, s64, 0x40000
	s_or_b32 s69, s65, 0x40000
	s_or_b32 s70, s66, 0x40000
	s_or_b32 s71, s67, 0x40000
	v_cmp_le_u32_e64 s[76:77], s68, v17
	v_cmp_le_u32_e64 s[78:79], s69, v18
	v_cmp_le_u32_e64 s[80:81], s70, v19
	v_cmp_le_u32_e64 s[82:83], s71, v20
	s_bcnt1_i32_b64 s72, s[76:77]
	s_bcnt1_i32_b64 s73, s[78:79]
	s_bcnt1_i32_b64 s74, s[80:81]
	s_bcnt1_i32_b64 s75, s[82:83]
	s_cmp_ge_u32 s72, 16
	s_cselect_b32 s64, s68, s64
	s_cselect_b32 s94, s72, s94
	s_cmp_ge_u32 s73, 16
	s_cselect_b32 s65, s69, s65
	s_cselect_b32 s95, s73, s95
	s_cmp_ge_u32 s74, 16
	s_cselect_b32 s66, s70, s66
	s_cselect_b32 s96, s74, s96
	s_cmp_ge_u32 s75, 16
	s_cselect_b32 s67, s71, s67
	s_cselect_b32 s97, s75, s97
	s_xor_b32 s84, s94, 16
	s_xor_b32 s85, s95, 16
	s_or_b32 s84, s84, s85
	s_xor_b32 s85, s96, 16
	s_or_b32 s84, s84, s85
	s_xor_b32 s85, s97, 16
	s_or_b32 s84, s84, s85
	s_cmp_eq_u32 s84, 0
	s_cbranch_scc1 .Lrk2_found
	s_or_b32 s68, s64, 0x20000
	s_or_b32 s69, s65, 0x20000
	s_or_b32 s70, s66, 0x20000
	s_or_b32 s71, s67, 0x20000
	v_cmp_le_u32_e64 s[76:77], s68, v17
	v_cmp_le_u32_e64 s[78:79], s69, v18
	v_cmp_le_u32_e64 s[80:81], s70, v19
	v_cmp_le_u32_e64 s[82:83], s71, v20
	s_bcnt1_i32_b64 s72, s[76:77]
	s_bcnt1_i32_b64 s73, s[78:79]
	s_bcnt1_i32_b64 s74, s[80:81]
	s_bcnt1_i32_b64 s75, s[82:83]
	s_cmp_ge_u32 s72, 16
	s_cselect_b32 s64, s68, s64
	s_cselect_b32 s94, s72, s94
	s_cmp_ge_u32 s73, 16
	s_cselect_b32 s65, s69, s65
	s_cselect_b32 s95, s73, s95
	s_cmp_ge_u32 s74, 16
	s_cselect_b32 s66, s70, s66
	s_cselect_b32 s96, s74, s96
	s_cmp_ge_u32 s75, 16
	s_cselect_b32 s67, s71, s67
	s_cselect_b32 s97, s75, s97
	s_or_b32 s68, s64, 0x10000
	s_or_b32 s69, s65, 0x10000
	s_or_b32 s70, s66, 0x10000
	s_or_b32 s71, s67, 0x10000
	v_cmp_le_u32_e64 s[76:77], s68, v17
	v_cmp_le_u32_e64 s[78:79], s69, v18
	v_cmp_le_u32_e64 s[80:81], s70, v19
	v_cmp_le_u32_e64 s[82:83], s71, v20
	s_bcnt1_i32_b64 s72, s[76:77]
	s_bcnt1_i32_b64 s73, s[78:79]
	s_bcnt1_i32_b64 s74, s[80:81]
	s_bcnt1_i32_b64 s75, s[82:83]
	s_cmp_ge_u32 s72, 16
	s_cselect_b32 s64, s68, s64
	s_cselect_b32 s94, s72, s94
	s_cmp_ge_u32 s73, 16
	s_cselect_b32 s65, s69, s65
	s_cselect_b32 s95, s73, s95
	s_cmp_ge_u32 s74, 16
	s_cselect_b32 s66, s70, s66
	s_cselect_b32 s96, s74, s96
	s_cmp_ge_u32 s75, 16
	s_cselect_b32 s67, s71, s67
	s_cselect_b32 s97, s75, s97
	s_xor_b32 s84, s94, 16
	s_xor_b32 s85, s95, 16
	s_or_b32 s84, s84, s85
	s_xor_b32 s85, s96, 16
	s_or_b32 s84, s84, s85
	s_xor_b32 s85, s97, 16
	s_or_b32 s84, s84, s85
	s_cmp_eq_u32 s84, 0
	s_cbranch_scc1 .Lrk2_found
	s_or_b32 s68, s64, 0x8000
	s_or_b32 s69, s65, 0x8000
	s_or_b32 s70, s66, 0x8000
	s_or_b32 s71, s67, 0x8000
	v_cmp_le_u32_e64 s[76:77], s68, v17
	v_cmp_le_u32_e64 s[78:79], s69, v18
	v_cmp_le_u32_e64 s[80:81], s70, v19
	v_cmp_le_u32_e64 s[82:83], s71, v20
	s_bcnt1_i32_b64 s72, s[76:77]
	s_bcnt1_i32_b64 s73, s[78:79]
	s_bcnt1_i32_b64 s74, s[80:81]
	s_bcnt1_i32_b64 s75, s[82:83]
	s_cmp_ge_u32 s72, 16
	s_cselect_b32 s64, s68, s64
	s_cselect_b32 s94, s72, s94
	s_cmp_ge_u32 s73, 16
	s_cselect_b32 s65, s69, s65
	s_cselect_b32 s95, s73, s95
	s_cmp_ge_u32 s74, 16
	s_cselect_b32 s66, s70, s66
	s_cselect_b32 s96, s74, s96
	s_cmp_ge_u32 s75, 16
	s_cselect_b32 s67, s71, s67
	s_cselect_b32 s97, s75, s97
	s_or_b32 s68, s64, 0x4000
	s_or_b32 s69, s65, 0x4000
	s_or_b32 s70, s66, 0x4000
	s_or_b32 s71, s67, 0x4000
	v_cmp_le_u32_e64 s[76:77], s68, v17
	v_cmp_le_u32_e64 s[78:79], s69, v18
	v_cmp_le_u32_e64 s[80:81], s70, v19
	v_cmp_le_u32_e64 s[82:83], s71, v20
	s_bcnt1_i32_b64 s72, s[76:77]
	s_bcnt1_i32_b64 s73, s[78:79]
	s_bcnt1_i32_b64 s74, s[80:81]
	s_bcnt1_i32_b64 s75, s[82:83]
	s_cmp_ge_u32 s72, 16
	s_cselect_b32 s64, s68, s64
	s_cselect_b32 s94, s72, s94
	s_cmp_ge_u32 s73, 16
	s_cselect_b32 s65, s69, s65
	s_cselect_b32 s95, s73, s95
	s_cmp_ge_u32 s74, 16
	s_cselect_b32 s66, s70, s66
	s_cselect_b32 s96, s74, s96
	s_cmp_ge_u32 s75, 16
	s_cselect_b32 s67, s71, s67
	s_cselect_b32 s97, s75, s97
	s_xor_b32 s84, s94, 16
	s_xor_b32 s85, s95, 16
	s_or_b32 s84, s84, s85
	s_xor_b32 s85, s96, 16
	s_or_b32 s84, s84, s85
	s_xor_b32 s85, s97, 16
	s_or_b32 s84, s84, s85
	s_cmp_eq_u32 s84, 0
	s_cbranch_scc1 .Lrk2_found
	s_or_b32 s68, s64, 0x2000
	s_or_b32 s69, s65, 0x2000
	s_or_b32 s70, s66, 0x2000
	s_or_b32 s71, s67, 0x2000
	v_cmp_le_u32_e64 s[76:77], s68, v17
	v_cmp_le_u32_e64 s[78:79], s69, v18
	v_cmp_le_u32_e64 s[80:81], s70, v19
	v_cmp_le_u32_e64 s[82:83], s71, v20
	s_bcnt1_i32_b64 s72, s[76:77]
	s_bcnt1_i32_b64 s73, s[78:79]
	s_bcnt1_i32_b64 s74, s[80:81]
	s_bcnt1_i32_b64 s75, s[82:83]
	s_cmp_ge_u32 s72, 16
	s_cselect_b32 s64, s68, s64
	s_cselect_b32 s94, s72, s94
	s_cmp_ge_u32 s73, 16
	s_cselect_b32 s65, s69, s65
	s_cselect_b32 s95, s73, s95
	s_cmp_ge_u32 s74, 16
	s_cselect_b32 s66, s70, s66
	s_cselect_b32 s96, s74, s96
	s_cmp_ge_u32 s75, 16
	s_cselect_b32 s67, s71, s67
	s_cselect_b32 s97, s75, s97
	s_or_b32 s68, s64, 0x1000
	s_or_b32 s69, s65, 0x1000
	s_or_b32 s70, s66, 0x1000
	s_or_b32 s71, s67, 0x1000
	v_cmp_le_u32_e64 s[76:77], s68, v17
	v_cmp_le_u32_e64 s[78:79], s69, v18
	v_cmp_le_u32_e64 s[80:81], s70, v19
	v_cmp_le_u32_e64 s[82:83], s71, v20
	s_bcnt1_i32_b64 s72, s[76:77]
	s_bcnt1_i32_b64 s73, s[78:79]
	s_bcnt1_i32_b64 s74, s[80:81]
	s_bcnt1_i32_b64 s75, s[82:83]
	s_cmp_ge_u32 s72, 16
	s_cselect_b32 s64, s68, s64
	s_cselect_b32 s94, s72, s94
	s_cmp_ge_u32 s73, 16
	s_cselect_b32 s65, s69, s65
	s_cselect_b32 s95, s73, s95
	s_cmp_ge_u32 s74, 16
	s_cselect_b32 s66, s70, s66
	s_cselect_b32 s96, s74, s96
	s_cmp_ge_u32 s75, 16
	s_cselect_b32 s67, s71, s67
	s_cselect_b32 s97, s75, s97
	s_xor_b32 s84, s94, 16
	s_xor_b32 s85, s95, 16
	s_or_b32 s84, s84, s85
	s_xor_b32 s85, s96, 16
	s_or_b32 s84, s84, s85
	s_xor_b32 s85, s97, 16
	s_or_b32 s84, s84, s85
	s_cmp_eq_u32 s84, 0
	s_cbranch_scc1 .Lrk2_found
	s_or_b32 s68, s64, 0x800
	s_or_b32 s69, s65, 0x800
	s_or_b32 s70, s66, 0x800
	s_or_b32 s71, s67, 0x800
	v_cmp_le_u32_e64 s[76:77], s68, v17
	v_cmp_le_u32_e64 s[78:79], s69, v18
	v_cmp_le_u32_e64 s[80:81], s70, v19
	v_cmp_le_u32_e64 s[82:83], s71, v20
	s_bcnt1_i32_b64 s72, s[76:77]
	s_bcnt1_i32_b64 s73, s[78:79]
	s_bcnt1_i32_b64 s74, s[80:81]
	s_bcnt1_i32_b64 s75, s[82:83]
	s_cmp_ge_u32 s72, 16
	s_cselect_b32 s64, s68, s64
	s_cselect_b32 s94, s72, s94
	s_cmp_ge_u32 s73, 16
	s_cselect_b32 s65, s69, s65
	s_cselect_b32 s95, s73, s95
	s_cmp_ge_u32 s74, 16
	s_cselect_b32 s66, s70, s66
	s_cselect_b32 s96, s74, s96
	s_cmp_ge_u32 s75, 16
	s_cselect_b32 s67, s71, s67
	s_cselect_b32 s97, s75, s97
	s_or_b32 s68, s64, 0x400
	s_or_b32 s69, s65, 0x400
	s_or_b32 s70, s66, 0x400
	s_or_b32 s71, s67, 0x400
	v_cmp_le_u32_e64 s[76:77], s68, v17
	v_cmp_le_u32_e64 s[78:79], s69, v18
	v_cmp_le_u32_e64 s[80:81], s70, v19
	v_cmp_le_u32_e64 s[82:83], s71, v20
	s_bcnt1_i32_b64 s72, s[76:77]
	s_bcnt1_i32_b64 s73, s[78:79]
	s_bcnt1_i32_b64 s74, s[80:81]
	s_bcnt1_i32_b64 s75, s[82:83]
	s_cmp_ge_u32 s72, 16
	s_cselect_b32 s64, s68, s64
	s_cselect_b32 s94, s72, s94
	s_cmp_ge_u32 s73, 16
	s_cselect_b32 s65, s69, s65
	s_cselect_b32 s95, s73, s95
	s_cmp_ge_u32 s74, 16
	s_cselect_b32 s66, s70, s66
	s_cselect_b32 s96, s74, s96
	s_cmp_ge_u32 s75, 16
	s_cselect_b32 s67, s71, s67
	s_cselect_b32 s97, s75, s97
	s_xor_b32 s84, s94, 16
	s_xor_b32 s85, s95, 16
	s_or_b32 s84, s84, s85
	s_xor_b32 s85, s96, 16
	s_or_b32 s84, s84, s85
	s_xor_b32 s85, s97, 16
	s_or_b32 s84, s84, s85
	s_cmp_eq_u32 s84, 0
	s_cbranch_scc1 .Lrk2_found
	s_or_b32 s68, s64, 0x200
	s_or_b32 s69, s65, 0x200
	s_or_b32 s70, s66, 0x200
	s_or_b32 s71, s67, 0x200
	v_cmp_le_u32_e64 s[76:77], s68, v17
	v_cmp_le_u32_e64 s[78:79], s69, v18
	v_cmp_le_u32_e64 s[80:81], s70, v19
	v_cmp_le_u32_e64 s[82:83], s71, v20
	s_bcnt1_i32_b64 s72, s[76:77]
	s_bcnt1_i32_b64 s73, s[78:79]
	s_bcnt1_i32_b64 s74, s[80:81]
	s_bcnt1_i32_b64 s75, s[82:83]
	s_cmp_ge_u32 s72, 16
	s_cselect_b32 s64, s68, s64
	s_cselect_b32 s94, s72, s94
	s_cmp_ge_u32 s73, 16
	s_cselect_b32 s65, s69, s65
	s_cselect_b32 s95, s73, s95
	s_cmp_ge_u32 s74, 16
	s_cselect_b32 s66, s70, s66
	s_cselect_b32 s96, s74, s96
	s_cmp_ge_u32 s75, 16
	s_cselect_b32 s67, s71, s67
	s_cselect_b32 s97, s75, s97
	s_or_b32 s68, s64, 0x100
	s_or_b32 s69, s65, 0x100
	s_or_b32 s70, s66, 0x100
	s_or_b32 s71, s67, 0x100
	v_cmp_le_u32_e64 s[76:77], s68, v17
	v_cmp_le_u32_e64 s[78:79], s69, v18
	v_cmp_le_u32_e64 s[80:81], s70, v19
	v_cmp_le_u32_e64 s[82:83], s71, v20
	s_bcnt1_i32_b64 s72, s[76:77]
	s_bcnt1_i32_b64 s73, s[78:79]
	s_bcnt1_i32_b64 s74, s[80:81]
	s_bcnt1_i32_b64 s75, s[82:83]
	s_cmp_ge_u32 s72, 16
	s_cselect_b32 s64, s68, s64
	s_cselect_b32 s94, s72, s94
	s_cmp_ge_u32 s73, 16
	s_cselect_b32 s65, s69, s65
	s_cselect_b32 s95, s73, s95
	s_cmp_ge_u32 s74, 16
	s_cselect_b32 s66, s70, s66
	s_cselect_b32 s96, s74, s96
	s_cmp_ge_u32 s75, 16
	s_cselect_b32 s67, s71, s67
	s_cselect_b32 s97, s75, s97
	s_xor_b32 s84, s94, 16
	s_xor_b32 s85, s95, 16
	s_or_b32 s84, s84, s85
	s_xor_b32 s85, s96, 16
	s_or_b32 s84, s84, s85
	s_xor_b32 s85, s97, 16
	s_or_b32 s84, s84, s85
	s_cmp_eq_u32 s84, 0
	s_cbranch_scc1 .Lrk2_found
	s_or_b32 s68, s64, 0x80
	s_or_b32 s69, s65, 0x80
	s_or_b32 s70, s66, 0x80
	s_or_b32 s71, s67, 0x80
	v_cmp_le_u32_e64 s[76:77], s68, v17
	v_cmp_le_u32_e64 s[78:79], s69, v18
	v_cmp_le_u32_e64 s[80:81], s70, v19
	v_cmp_le_u32_e64 s[82:83], s71, v20
	s_bcnt1_i32_b64 s72, s[76:77]
	s_bcnt1_i32_b64 s73, s[78:79]
	s_bcnt1_i32_b64 s74, s[80:81]
	s_bcnt1_i32_b64 s75, s[82:83]
	s_cmp_ge_u32 s72, 16
	s_cselect_b32 s64, s68, s64
	s_cselect_b32 s94, s72, s94
	s_cmp_ge_u32 s73, 16
	s_cselect_b32 s65, s69, s65
	s_cselect_b32 s95, s73, s95
	s_cmp_ge_u32 s74, 16
	s_cselect_b32 s66, s70, s66
	s_cselect_b32 s96, s74, s96
	s_cmp_ge_u32 s75, 16
	s_cselect_b32 s67, s71, s67
	s_cselect_b32 s97, s75, s97
	s_or_b32 s68, s64, 0x40
	s_or_b32 s69, s65, 0x40
	s_or_b32 s70, s66, 0x40
	s_or_b32 s71, s67, 0x40
	v_cmp_le_u32_e64 s[76:77], s68, v17
	v_cmp_le_u32_e64 s[78:79], s69, v18
	v_cmp_le_u32_e64 s[80:81], s70, v19
	v_cmp_le_u32_e64 s[82:83], s71, v20
	s_bcnt1_i32_b64 s72, s[76:77]
	s_bcnt1_i32_b64 s73, s[78:79]
	s_bcnt1_i32_b64 s74, s[80:81]
	s_bcnt1_i32_b64 s75, s[82:83]
	s_cmp_ge_u32 s72, 16
	s_cselect_b32 s64, s68, s64
	s_cselect_b32 s94, s72, s94
	s_cmp_ge_u32 s73, 16
	s_cselect_b32 s65, s69, s65
	s_cselect_b32 s95, s73, s95
	s_cmp_ge_u32 s74, 16
	s_cselect_b32 s66, s70, s66
	s_cselect_b32 s96, s74, s96
	s_cmp_ge_u32 s75, 16
	s_cselect_b32 s67, s71, s67
	s_cselect_b32 s97, s75, s97
	s_xor_b32 s84, s94, 16
	s_xor_b32 s85, s95, 16
	s_or_b32 s84, s84, s85
	s_xor_b32 s85, s96, 16
	s_or_b32 s84, s84, s85
	s_xor_b32 s85, s97, 16
	s_or_b32 s84, s84, s85
	s_cmp_eq_u32 s84, 0
	s_cbranch_scc1 .Lrk2_found
	s_or_b32 s68, s64, 0x20
	s_or_b32 s69, s65, 0x20
	s_or_b32 s70, s66, 0x20
	s_or_b32 s71, s67, 0x20
	v_cmp_le_u32_e64 s[76:77], s68, v17
	v_cmp_le_u32_e64 s[78:79], s69, v18
	v_cmp_le_u32_e64 s[80:81], s70, v19
	v_cmp_le_u32_e64 s[82:83], s71, v20
	s_bcnt1_i32_b64 s72, s[76:77]
	s_bcnt1_i32_b64 s73, s[78:79]
	s_bcnt1_i32_b64 s74, s[80:81]
	s_bcnt1_i32_b64 s75, s[82:83]
	s_cmp_ge_u32 s72, 16
	s_cselect_b32 s64, s68, s64
	s_cselect_b32 s94, s72, s94
	s_cmp_ge_u32 s73, 16
	s_cselect_b32 s65, s69, s65
	s_cselect_b32 s95, s73, s95
	s_cmp_ge_u32 s74, 16
	s_cselect_b32 s66, s70, s66
	s_cselect_b32 s96, s74, s96
	s_cmp_ge_u32 s75, 16
	s_cselect_b32 s67, s71, s67
	s_cselect_b32 s97, s75, s97
	s_or_b32 s68, s64, 0x10
	s_or_b32 s69, s65, 0x10
	s_or_b32 s70, s66, 0x10
	s_or_b32 s71, s67, 0x10
	v_cmp_le_u32_e64 s[76:77], s68, v17
	v_cmp_le_u32_e64 s[78:79], s69, v18
	v_cmp_le_u32_e64 s[80:81], s70, v19
	v_cmp_le_u32_e64 s[82:83], s71, v20
	s_bcnt1_i32_b64 s72, s[76:77]
	s_bcnt1_i32_b64 s73, s[78:79]
	s_bcnt1_i32_b64 s74, s[80:81]
	s_bcnt1_i32_b64 s75, s[82:83]
	s_cmp_ge_u32 s72, 16
	s_cselect_b32 s64, s68, s64
	s_cselect_b32 s94, s72, s94
	s_cmp_ge_u32 s73, 16
	s_cselect_b32 s65, s69, s65
	s_cselect_b32 s95, s73, s95
	s_cmp_ge_u32 s74, 16
	s_cselect_b32 s66, s70, s66
	s_cselect_b32 s96, s74, s96
	s_cmp_ge_u32 s75, 16
	s_cselect_b32 s67, s71, s67
	s_cselect_b32 s97, s75, s97
	s_xor_b32 s84, s94, 16
	s_xor_b32 s85, s95, 16
	s_or_b32 s84, s84, s85
	s_xor_b32 s85, s96, 16
	s_or_b32 s84, s84, s85
	s_xor_b32 s85, s97, 16
	s_or_b32 s84, s84, s85
	s_cmp_eq_u32 s84, 0
	s_cbranch_scc1 .Lrk2_found
	s_or_b32 s68, s64, 0x8
	s_or_b32 s69, s65, 0x8
	s_or_b32 s70, s66, 0x8
	s_or_b32 s71, s67, 0x8
	v_cmp_le_u32_e64 s[76:77], s68, v17
	v_cmp_le_u32_e64 s[78:79], s69, v18
	v_cmp_le_u32_e64 s[80:81], s70, v19
	v_cmp_le_u32_e64 s[82:83], s71, v20
	s_bcnt1_i32_b64 s72, s[76:77]
	s_bcnt1_i32_b64 s73, s[78:79]
	s_bcnt1_i32_b64 s74, s[80:81]
	s_bcnt1_i32_b64 s75, s[82:83]
	s_cmp_ge_u32 s72, 16
	s_cselect_b32 s64, s68, s64
	s_cselect_b32 s94, s72, s94
	s_cmp_ge_u32 s73, 16
	s_cselect_b32 s65, s69, s65
	s_cselect_b32 s95, s73, s95
	s_cmp_ge_u32 s74, 16
	s_cselect_b32 s66, s70, s66
	s_cselect_b32 s96, s74, s96
	s_cmp_ge_u32 s75, 16
	s_cselect_b32 s67, s71, s67
	s_cselect_b32 s97, s75, s97
	s_or_b32 s68, s64, 0x4
	s_or_b32 s69, s65, 0x4
	s_or_b32 s70, s66, 0x4
	s_or_b32 s71, s67, 0x4
	v_cmp_le_u32_e64 s[76:77], s68, v17
	v_cmp_le_u32_e64 s[78:79], s69, v18
	v_cmp_le_u32_e64 s[80:81], s70, v19
	v_cmp_le_u32_e64 s[82:83], s71, v20
	s_bcnt1_i32_b64 s72, s[76:77]
	s_bcnt1_i32_b64 s73, s[78:79]
	s_bcnt1_i32_b64 s74, s[80:81]
	s_bcnt1_i32_b64 s75, s[82:83]
	s_cmp_ge_u32 s72, 16
	s_cselect_b32 s64, s68, s64
	s_cselect_b32 s94, s72, s94
	s_cmp_ge_u32 s73, 16
	s_cselect_b32 s65, s69, s65
	s_cselect_b32 s95, s73, s95
	s_cmp_ge_u32 s74, 16
	s_cselect_b32 s66, s70, s66
	s_cselect_b32 s96, s74, s96
	s_cmp_ge_u32 s75, 16
	s_cselect_b32 s67, s71, s67
	s_cselect_b32 s97, s75, s97
	s_xor_b32 s84, s94, 16
	s_xor_b32 s85, s95, 16
	s_or_b32 s84, s84, s85
	s_xor_b32 s85, s96, 16
	s_or_b32 s84, s84, s85
	s_xor_b32 s85, s97, 16
	s_or_b32 s84, s84, s85
	s_cmp_eq_u32 s84, 0
	s_cbranch_scc1 .Lrk2_found
	s_or_b32 s68, s64, 0x2
	s_or_b32 s69, s65, 0x2
	s_or_b32 s70, s66, 0x2
	s_or_b32 s71, s67, 0x2
	v_cmp_le_u32_e64 s[76:77], s68, v17
	v_cmp_le_u32_e64 s[78:79], s69, v18
	v_cmp_le_u32_e64 s[80:81], s70, v19
	v_cmp_le_u32_e64 s[82:83], s71, v20
	s_bcnt1_i32_b64 s72, s[76:77]
	s_bcnt1_i32_b64 s73, s[78:79]
	s_bcnt1_i32_b64 s74, s[80:81]
	s_bcnt1_i32_b64 s75, s[82:83]
	s_cmp_ge_u32 s72, 16
	s_cselect_b32 s64, s68, s64
	s_cselect_b32 s94, s72, s94
	s_cmp_ge_u32 s73, 16
	s_cselect_b32 s65, s69, s65
	s_cselect_b32 s95, s73, s95
	s_cmp_ge_u32 s74, 16
	s_cselect_b32 s66, s70, s66
	s_cselect_b32 s96, s74, s96
	s_cmp_ge_u32 s75, 16
	s_cselect_b32 s67, s71, s67
	s_cselect_b32 s97, s75, s97
	s_or_b32 s68, s64, 0x1
	s_or_b32 s69, s65, 0x1
	s_or_b32 s70, s66, 0x1
	s_or_b32 s71, s67, 0x1
	v_cmp_le_u32_e64 s[76:77], s68, v17
	v_cmp_le_u32_e64 s[78:79], s69, v18
	v_cmp_le_u32_e64 s[80:81], s70, v19
	v_cmp_le_u32_e64 s[82:83], s71, v20
	s_bcnt1_i32_b64 s72, s[76:77]
	s_bcnt1_i32_b64 s73, s[78:79]
	s_bcnt1_i32_b64 s74, s[80:81]
	s_bcnt1_i32_b64 s75, s[82:83]
	s_cmp_ge_u32 s72, 16
	s_cselect_b32 s64, s68, s64
	s_cselect_b32 s94, s72, s94
	s_cmp_ge_u32 s73, 16
	s_cselect_b32 s65, s69, s65
	s_cselect_b32 s95, s73, s95
	s_cmp_ge_u32 s74, 16
	s_cselect_b32 s66, s70, s66
	s_cselect_b32 s96, s74, s96
	s_cmp_ge_u32 s75, 16
	s_cselect_b32 s67, s71, s67
	s_cselect_b32 s97, s75, s97
